# v126 plus packing of the scalar -log2e multiplies and 1.0+e adds of the SwiGLU / silu / gate epilogues (P1, P9, P3) into v_pk_mul_f32 / v_pk_add_f32 (bit-identical)
# baseline (speedup 1.0000x reference)
.LBB0_132:
	s_andn2_b64 vcc, exec, s[0:1]
	s_barrier
	s_cbranch_vccnz .LBB0_134
	v_lshrrev_b32_e32 v18, 2, v0
	s_add_u32 s0, s86, 0x113000
	v_and_b32_e32 v18, 12, v18
	s_addc_u32 s1, s87, 0
	v_lshlrev_b32_e32 v19, 6, v18
	global_load_dword v20, v19, s[0:1]
	v_or_b32_e32 v21, 64, v19
	v_or_b32_e32 v22, 0x80, v19
	v_or_b32_e32 v19, 0xc0, v19
	global_load_dword v21, v21, s[0:1]
	s_nop 0
	global_load_dword v22, v22, s[0:1]
	s_nop 0
	global_load_dword v19, v19, s[0:1]
	v_mov_b32_e32 v24, 0x358637bd
	s_mov_b32 s8, 0x800000
	v_or_b32_e32 v23, s4, v1
	v_or_b32_e32 v1, s5, v1
	s_movk_i32 s9, 0x7fff
	s_movk_i32 s10, 0xb00
	s_add_u32 s6, s86, 0x113400
	v_mul_u32_u24_e32 v26, 0xb00, v18
	v_mad_u32_u24 v27, v18, s10, s10
	s_addc_u32 s7, s87, 0
	v_add_lshl_u32 v28, v23, v26, 1
	v_add_lshl_u32 v26, v1, v26, 1
	v_add_lshl_u32 v29, v23, v27, 1
	v_add_lshl_u32 v27, v1, v27, 1
	v_mov_b32_e32 v25, 0x1600
	v_mad_u32_u24 v25, v18, s10, v25
	s_waitcnt vmcnt(3)
	v_fmamk_f32 v20, v20, 0x3a800000, v24
	v_mul_f32_e32 v30, 0x4b800000, v20
	s_waitcnt vmcnt(2)
	v_fmamk_f32 v21, v21, 0x3a800000, v24
	v_cmp_gt_f32_e32 vcc, s8, v20
	s_waitcnt vmcnt(1)
	v_fmamk_f32 v22, v22, 0x3a800000, v24
	s_waitcnt vmcnt(0)
	v_fmac_f32_e32 v24, 0x3a800000, v19
	v_cndmask_b32_e32 v19, v20, v30, vcc
	v_mul_f32_e32 v20, 0x4b800000, v21
	v_cmp_gt_f32_e64 s[0:1], s8, v21
	v_mul_f32_e32 v30, 0x4b800000, v22
	v_rsq_f32_e32 v19, v19
	v_cndmask_b32_e64 v20, v21, v20, s[0:1]
	v_cmp_gt_f32_e64 s[4:5], s8, v22
	v_rsq_f32_e32 v20, v20
	s_nop 0
	v_cndmask_b32_e64 v21, v22, v30, s[4:5]
	v_rsq_f32_e32 v21, v21
	v_mul_f32_e32 v22, 0x45800000, v19
	v_cndmask_b32_e32 v19, v19, v22, vcc
	v_mul_f32_e32 v22, 0x45800000, v20
	v_mul_f32_e32 v30, 0x45800000, v21
	v_mul_f32_e32 v14, v14, v19
	v_mul_f32_e32 v6, v6, v19
	v_mul_f32_e32 v10, v10, v19
	v_mul_f32_e32 v2, v2, v19
	v_cndmask_b32_e64 v19, v20, v22, s[0:1]
	v_cndmask_b32_e64 v20, v21, v30, s[4:5]
	v_mul_f32_e32 v21, 0xbfb8aa3b, v14
	v_mul_f32_e32 v22, 0xbfb8aa3b, v10
	v_mul_f32_e32 v15, v15, v19
	v_mul_f32_e32 v7, v7, v19
	v_mul_f32_e32 v11, v11, v19
	v_mul_f32_e32 v3, v3, v19
	v_mul_f32_e32 v16, v16, v20
	v_exp_f32_e32 v19, v21
	v_exp_f32_e32 v21, v22
	v_mul_f32_e32 v22, 0xbfb8aa3b, v15
	v_mul_f32_e32 v30, 0xbfb8aa3b, v11
	v_mul_f32_e32 v31, 0xbfb8aa3b, v16
	v_exp_f32_e32 v22, v22
	v_exp_f32_e32 v30, v30
	v_exp_f32_e32 v31, v31
	v_add_f32_e32 v19, 1.0, v19
	v_add_f32_e32 v21, 1.0, v21
	v_rcp_f32_e32 v19, v19
	v_rcp_f32_e32 v21, v21
	v_add_f32_e32 v22, 1.0, v22
	v_pk_add_f32 v[30:31], v[30:31], 1.0 op_sel_hi:[1,0]
	v_rcp_f32_e32 v22, v22
	v_rcp_f32_e32 v30, v30
	v_rcp_f32_e32 v31, v31
	v_mul_f32_e32 v14, v14, v19
	v_mul_f32_e32 v10, v10, v21
	v_mul_f32_e32 v6, v6, v14
	v_mul_f32_e32 v2, v2, v10
	v_mul_f32_e32 v10, v15, v22
	v_mul_f32_e32 v11, v11, v30
	v_mul_f32_e32 v14, v16, v31
	v_bfe_u32 v15, v6, 16, 1
	v_bfe_u32 v16, v2, 16, 1
	v_mul_f32_e32 v7, v7, v10
	v_mul_f32_e32 v3, v3, v11
	v_add3_u32 v6, v6, v15, s9
	v_add3_u32 v2, v2, v16, s9
	v_bfe_u32 v10, v7, 16, 1
	v_bfe_u32 v11, v3, 16, 1
	global_store_short_d16_hi v28, v6, s[6:7]
	global_store_short_d16_hi v26, v2, s[6:7]
	v_add3_u32 v2, v7, v10, s9
	v_add3_u32 v3, v3, v11, s9
	global_store_short_d16_hi v29, v2, s[6:7]
	global_store_short_d16_hi v27, v3, s[6:7]
	v_mul_f32_e32 v2, 0x4b800000, v24
	v_cmp_gt_f32_e32 vcc, s8, v24
	v_mul_f32_e32 v8, v8, v20
	v_mul_f32_e32 v8, v8, v14
	v_cndmask_b32_e32 v2, v24, v2, vcc
	v_rsq_f32_e32 v2, v2
	v_mul_f32_e32 v12, v12, v20
	v_bfe_u32 v14, v8, 16, 1
	v_mul_f32_e32 v32, 0xbfb8aa3b, v12
	v_add3_u32 v6, v8, v14, s9
	v_add_lshl_u32 v3, v23, v25, 1
	v_exp_f32_e32 v32, v32
	global_store_short_d16_hi v3, v6, s[6:7]
	v_mul_f32_e32 v6, 0x45800000, v2
	v_cndmask_b32_e32 v2, v2, v6, vcc
	v_mul_f32_e32 v6, v17, v2
	v_mul_f32_e32 v7, 0xbfb8aa3b, v6
	v_add_f32_e32 v32, 1.0, v32
	v_exp_f32_e32 v7, v7
	v_rcp_f32_e32 v32, v32
	v_mul_f32_e32 v4, v4, v20
	v_add_f32_e32 v7, 1.0, v7
	v_mul_f32_e32 v3, v12, v32
	v_rcp_f32_e32 v7, v7
	v_mul_f32_e32 v3, v4, v3
	v_bfe_u32 v4, v3, 16, 1
	v_add3_u32 v3, v3, v4, s9
	v_add_lshl_u32 v4, v1, v25, 1
	global_store_short_d16_hi v4, v3, s[6:7]
	v_mul_f32_e32 v3, v6, v7
	v_mul_f32_e32 v4, v9, v2
	v_mul_f32_e32 v3, v4, v3
	v_mul_f32_e32 v4, v13, v2
	v_mul_f32_e32 v6, 0xbfb8aa3b, v4
	v_exp_f32_e32 v6, v6
	v_bfe_u32 v7, v3, 16, 1
	v_add3_u32 v3, v3, v7, s9
	v_mov_b32_e32 v7, 0x2100
	v_add_f32_e32 v6, 1.0, v6
	v_rcp_f32_e32 v6, v6
	v_mad_u32_u24 v7, v18, s10, v7
	v_add_lshl_u32 v8, v23, v7, 1
	global_store_short_d16_hi v8, v3, s[6:7]
	v_mul_f32_e32 v3, v4, v6
	v_mul_f32_e32 v2, v5, v2
	v_mul_f32_e32 v2, v2, v3
	v_bfe_u32 v3, v2, 16, 1
	v_add3_u32 v2, v2, v3, s9
	v_add_lshl_u32 v1, v1, v7, 1
	global_store_short_d16_hi v1, v2, s[6:7]

.LBB0_285:
	v_lshl_add_u32 v131, s39, 10, v220
	ds_read2_b32 v[134:135], v131 offset1:16
	v_lshl_or_b32 v132, s93, 7, v219
	v_lshl_add_u32 v130, s38, 8, v1
	v_ashrrev_i32_e32 v133, 31, v132
	s_mov_b64 s[38:39], -1
	s_waitcnt lgkmcnt(0)
	v_pk_mul_f32 v[122:123], v[122:123], v[134:135] op_sel_hi:[1,0]
	v_pk_mul_f32 v[126:127], v[126:127], v[134:135] op_sel_hi:[1,0]
	s_mov_b32 s32, 0xbfb8aa3b
	v_pk_mul_f32 v[136:137], v[122:123], s[32:33] op_sel_hi:[1,0]
	v_exp_f32_e32 v136, v136
	v_exp_f32_e32 v137, v137
	v_pk_mul_f32 v[124:125], v[124:125], v[134:135] op_sel_hi:[1,0]
	v_pk_mul_f32 v[114:115], v[114:115], v[134:135] op_sel_hi:[1,0]
	v_pk_add_f32 v[136:137], v[136:137], 1.0 op_sel_hi:[1,0]
	v_rcp_f32_e32 v136, v136
	v_rcp_f32_e32 v137, v137
	v_pk_mul_f32 v[118:119], v[118:119], v[134:135] op_sel_hi:[1,0]
	v_pk_mul_f32 v[116:117], v[116:117], v[134:135] op_sel_hi:[1,0]
	v_pk_mul_f32 v[120:121], v[120:121], v[134:135] op_sel_hi:[1,0]
	v_pk_mul_f32 v[122:123], v[122:123], v[136:137]
	v_pk_mul_f32 v[128:129], v[128:129], v[134:135] op_sel_hi:[1,0]
	v_pk_mul_f32 v[122:123], v[126:127], v[122:123]
	v_pk_mul_f32 v[126:127], v[124:125], s[32:33] op_sel_hi:[1,0]
	v_exp_f32_e32 v126, v126
	v_exp_f32_e32 v127, v127
	s_andn2_b64 vcc, exec, s[4:5]
	v_pk_add_f32 v[126:127], v[126:127], 1.0 op_sel_hi:[1,0]
	v_rcp_f32_e32 v126, v126
	v_rcp_f32_e32 v127, v127
	s_nop 0
	v_pk_mul_f32 v[124:125], v[124:125], v[126:127]
	v_pk_mul_f32 v[126:127], v[114:115], s[32:33] op_sel_hi:[1,0]
	v_exp_f32_e32 v126, v126
	v_exp_f32_e32 v127, v127
	v_pk_mul_f32 v[124:125], v[128:129], v[124:125]
	v_pk_add_f32 v[126:127], v[126:127], 1.0 op_sel_hi:[1,0]
	v_rcp_f32_e32 v126, v126
	v_rcp_f32_e32 v127, v127
	s_nop 0
	v_pk_mul_f32 v[114:115], v[114:115], v[126:127]
	s_nop 0
	v_pk_mul_f32 v[114:115], v[118:119], v[114:115]
	v_pk_mul_f32 v[118:119], v[116:117], s[32:33] op_sel_hi:[1,0]
	v_exp_f32_e32 v118, v118
	v_exp_f32_e32 v119, v119
	s_nop 0
	v_pk_add_f32 v[118:119], v[118:119], 1.0 op_sel_hi:[1,0]
	v_rcp_f32_e32 v118, v118
	v_rcp_f32_e32 v119, v119
	s_nop 0
	v_pk_mul_f32 v[116:117], v[116:117], v[118:119]
	s_nop 0
	v_pk_mul_f32 v[116:117], v[120:121], v[116:117]
	v_cvt_pk_bf16_f32 v120, v114, v115
	v_mov_b64_e32 v[114:115], s[54:55]
	v_cvt_pk_bf16_f32 v118, v122, v123
	v_cvt_pk_bf16_f32 v121, v116, v117
	v_mad_i64_i32 v[122:123], s[18:19], v130, s67, v[114:115]
	v_lshlrev_b64 v[116:117], 1, v[132:133]
	v_cvt_pk_bf16_f32 v119, v124, v125
	v_lshl_add_u64 v[122:123], v[122:123], 0, v[116:117]
	global_store_dwordx4 v[122:123], v[118:121], off sc0 sc1
	s_nop 1
	v_mov_b32_e32 v118, v135
	v_pk_mul_f32 v[106:107], v[106:107], v[118:119] op_sel_hi:[1,0]
	s_nop 0
	v_mul_f32_e32 v119, 0xbfb8aa3b, v106
	v_exp_f32_e32 v119, v119
	s_nop 0
	v_add_f32_e32 v119, 1.0, v119
	v_rcp_f32_e32 v120, v119
	v_pk_mul_f32 v[110:111], v[110:111], v[118:119] op_sel_hi:[1,0]
	v_mul_f32_e32 v119, 0xbfb8aa3b, v107
	v_exp_f32_e32 v119, v119
	s_nop 0
	v_add_f32_e32 v119, 1.0, v119
	v_rcp_f32_e32 v121, v119
	v_pk_mul_f32 v[108:109], v[108:109], v[118:119] op_sel_hi:[1,0]
	v_pk_mul_f32 v[98:99], v[98:99], v[118:119] op_sel_hi:[1,0]
	v_pk_mul_f32 v[102:103], v[102:103], v[118:119] op_sel_hi:[1,0]
	v_pk_mul_f32 v[106:107], v[106:107], v[120:121]
	v_pk_mul_f32 v[112:113], v[112:113], v[118:119] op_sel_hi:[1,0]
	v_pk_mul_f32 v[106:107], v[110:111], v[106:107]
	v_pk_mul_f32 v[110:111], v[108:109], s[32:33] op_sel_hi:[1,0]
	v_exp_f32_e32 v110, v110
	v_exp_f32_e32 v111, v111
	v_pk_mul_f32 v[104:105], v[104:105], v[118:119] op_sel_hi:[1,0]
	v_pk_add_f32 v[110:111], v[110:111], 1.0 op_sel_hi:[1,0]
	v_rcp_f32_e32 v110, v110
	v_rcp_f32_e32 v111, v111
	s_nop 0
	v_pk_mul_f32 v[108:109], v[108:109], v[110:111]
	v_pk_mul_f32 v[110:111], v[98:99], s[32:33] op_sel_hi:[1,0]
	v_exp_f32_e32 v110, v110
	v_exp_f32_e32 v111, v111
	v_pk_mul_f32 v[108:109], v[112:113], v[108:109]
	v_pk_add_f32 v[110:111], v[110:111], 1.0 op_sel_hi:[1,0]
	v_rcp_f32_e32 v110, v110
	v_rcp_f32_e32 v111, v111
	s_nop 0
	v_pk_mul_f32 v[98:99], v[98:99], v[110:111]
	s_nop 0
	v_pk_mul_f32 v[102:103], v[102:103], v[98:99]
	v_pk_mul_f32 v[98:99], v[100:101], v[118:119] op_sel_hi:[1,0]
	v_or_b32_e32 v110, 16, v130
	v_pk_mul_f32 v[100:101], v[98:99], s[32:33] op_sel_hi:[1,0]
	v_exp_f32_e32 v100, v100
	v_exp_f32_e32 v101, v101
	s_nop 0
	v_pk_add_f32 v[100:101], v[100:101], 1.0 op_sel_hi:[1,0]
	v_rcp_f32_e32 v100, v100
	v_rcp_f32_e32 v101, v101
	s_nop 0
	v_pk_mul_f32 v[98:99], v[98:99], v[100:101]
	s_nop 0
	v_pk_mul_f32 v[104:105], v[104:105], v[98:99]
	v_cvt_pk_bf16_f32 v100, v102, v103
	v_mad_i64_i32 v[102:103], s[18:19], v110, s67, v[114:115]
	v_cvt_pk_bf16_f32 v98, v106, v107
	v_cvt_pk_bf16_f32 v99, v108, v109
	v_cvt_pk_bf16_f32 v101, v104, v105
	v_lshl_add_u64 v[102:103], v[102:103], 0, v[116:117]
	global_store_dwordx4 v[102:103], v[98:101], off sc0 sc1
	ds_read2_b32 v[98:99], v131 offset0:32 offset1:48
	s_waitcnt lgkmcnt(0)
	v_pk_mul_f32 v[90:91], v[90:91], v[98:99] op_sel_hi:[1,0]
	s_nop 0
	v_pk_mul_f32 v[100:101], v[90:91], s[32:33] op_sel_hi:[1,0]
	v_exp_f32_e32 v100, v100
	v_exp_f32_e32 v101, v101
	v_pk_mul_f32 v[94:95], v[94:95], v[98:99] op_sel_hi:[1,0]
	v_pk_mul_f32 v[92:93], v[92:93], v[98:99] op_sel_hi:[1,0]
	v_pk_add_f32 v[100:101], v[100:101], 1.0 op_sel_hi:[1,0]
	v_rcp_f32_e32 v100, v100
	v_rcp_f32_e32 v101, v101
	v_pk_mul_f32 v[82:83], v[82:83], v[98:99] op_sel_hi:[1,0]
	v_pk_mul_f32 v[86:87], v[86:87], v[98:99] op_sel_hi:[1,0]
	v_pk_mul_f32 v[96:97], v[96:97], v[98:99] op_sel_hi:[1,0]
	v_pk_mul_f32 v[90:91], v[90:91], v[100:101]
	v_pk_mul_f32 v[88:89], v[88:89], v[98:99] op_sel_hi:[1,0]
	v_pk_mul_f32 v[90:91], v[94:95], v[90:91]
	v_pk_mul_f32 v[94:95], v[92:93], s[32:33] op_sel_hi:[1,0]
	v_exp_f32_e32 v94, v94
	v_exp_f32_e32 v95, v95
	s_nop 0
	v_pk_add_f32 v[94:95], v[94:95], 1.0 op_sel_hi:[1,0]
	v_rcp_f32_e32 v94, v94
	v_rcp_f32_e32 v95, v95
	s_nop 0
	v_pk_mul_f32 v[92:93], v[92:93], v[94:95]
	v_pk_mul_f32 v[94:95], v[82:83], s[32:33] op_sel_hi:[1,0]
	v_exp_f32_e32 v94, v94
	v_exp_f32_e32 v95, v95
	v_pk_mul_f32 v[92:93], v[96:97], v[92:93]
	v_pk_add_f32 v[94:95], v[94:95], 1.0 op_sel_hi:[1,0]
	v_rcp_f32_e32 v94, v94
	v_rcp_f32_e32 v95, v95
	s_nop 0
	v_pk_mul_f32 v[82:83], v[82:83], v[94:95]
	s_nop 0
	v_pk_mul_f32 v[86:87], v[86:87], v[82:83]
	v_pk_mul_f32 v[82:83], v[84:85], v[98:99] op_sel_hi:[1,0]
	v_or_b32_e32 v94, 32, v130
	v_pk_mul_f32 v[84:85], v[82:83], s[32:33] op_sel_hi:[1,0]
	v_exp_f32_e32 v84, v84
	v_exp_f32_e32 v85, v85
	s_nop 0
	v_pk_add_f32 v[84:85], v[84:85], 1.0 op_sel_hi:[1,0]
	v_rcp_f32_e32 v84, v84
	v_rcp_f32_e32 v85, v85
	s_nop 0
	v_pk_mul_f32 v[82:83], v[82:83], v[84:85]
	s_nop 0
	v_pk_mul_f32 v[88:89], v[88:89], v[82:83]
	v_cvt_pk_bf16_f32 v84, v86, v87
	v_mad_i64_i32 v[86:87], s[18:19], v94, s67, v[114:115]
	v_cvt_pk_bf16_f32 v82, v90, v91
	v_cvt_pk_bf16_f32 v83, v92, v93
	v_cvt_pk_bf16_f32 v85, v88, v89
	v_lshl_add_u64 v[86:87], v[86:87], 0, v[116:117]
	global_store_dwordx4 v[86:87], v[82:85], off sc0 sc1
	s_nop 1
	v_mov_b32_e32 v82, v99
	v_pk_mul_f32 v[74:75], v[74:75], v[82:83] op_sel_hi:[1,0]
	s_nop 0
	v_mul_f32_e32 v83, 0xbfb8aa3b, v74
	v_exp_f32_e32 v83, v83
	s_nop 0
	v_add_f32_e32 v83, 1.0, v83
	v_rcp_f32_e32 v84, v83
	v_pk_mul_f32 v[78:79], v[78:79], v[82:83] op_sel_hi:[1,0]
	v_mul_f32_e32 v83, 0xbfb8aa3b, v75
	v_exp_f32_e32 v83, v83
	s_nop 0
	v_add_f32_e32 v83, 1.0, v83
	v_rcp_f32_e32 v85, v83
	v_pk_mul_f32 v[76:77], v[76:77], v[82:83] op_sel_hi:[1,0]
	v_pk_mul_f32 v[66:67], v[66:67], v[82:83] op_sel_hi:[1,0]
	v_pk_mul_f32 v[70:71], v[70:71], v[82:83] op_sel_hi:[1,0]
	v_pk_mul_f32 v[74:75], v[74:75], v[84:85]
	v_pk_mul_f32 v[80:81], v[80:81], v[82:83] op_sel_hi:[1,0]
	v_pk_mul_f32 v[74:75], v[78:79], v[74:75]
	v_pk_mul_f32 v[78:79], v[76:77], s[32:33] op_sel_hi:[1,0]
	v_exp_f32_e32 v78, v78
	v_exp_f32_e32 v79, v79
	v_pk_mul_f32 v[72:73], v[72:73], v[82:83] op_sel_hi:[1,0]
	v_pk_add_f32 v[78:79], v[78:79], 1.0 op_sel_hi:[1,0]
	v_rcp_f32_e32 v78, v78
	v_rcp_f32_e32 v79, v79
	s_nop 0
	v_pk_mul_f32 v[76:77], v[76:77], v[78:79]
	v_pk_mul_f32 v[78:79], v[66:67], s[32:33] op_sel_hi:[1,0]
	v_exp_f32_e32 v78, v78
	v_exp_f32_e32 v79, v79
	v_pk_mul_f32 v[76:77], v[80:81], v[76:77]
	v_pk_add_f32 v[78:79], v[78:79], 1.0 op_sel_hi:[1,0]
	v_rcp_f32_e32 v78, v78
	v_rcp_f32_e32 v79, v79
	s_nop 0
	v_pk_mul_f32 v[66:67], v[66:67], v[78:79]
	s_nop 0
	v_pk_mul_f32 v[70:71], v[70:71], v[66:67]
	v_pk_mul_f32 v[66:67], v[68:69], v[82:83] op_sel_hi:[1,0]
	v_or_b32_e32 v78, 48, v130
	v_pk_mul_f32 v[68:69], v[66:67], s[32:33] op_sel_hi:[1,0]
	v_exp_f32_e32 v68, v68
	v_exp_f32_e32 v69, v69
	s_nop 0
	v_pk_add_f32 v[68:69], v[68:69], 1.0 op_sel_hi:[1,0]
	v_rcp_f32_e32 v68, v68
	v_rcp_f32_e32 v69, v69
	s_nop 0
	v_pk_mul_f32 v[66:67], v[66:67], v[68:69]
	s_nop 0
	v_pk_mul_f32 v[72:73], v[72:73], v[66:67]
	v_cvt_pk_bf16_f32 v68, v70, v71
	v_mad_i64_i32 v[70:71], s[18:19], v78, s67, v[114:115]
	v_cvt_pk_bf16_f32 v66, v74, v75
	v_cvt_pk_bf16_f32 v67, v76, v77
	v_cvt_pk_bf16_f32 v69, v72, v73
	v_lshl_add_u64 v[70:71], v[70:71], 0, v[116:117]
	global_store_dwordx4 v[70:71], v[66:69], off sc0 sc1
	ds_read2_b32 v[66:67], v131 offset0:128 offset1:144
	v_add_u32_e32 v70, 0x80, v130
	s_waitcnt lgkmcnt(0)
	v_pk_mul_f32 v[58:59], v[58:59], v[66:67] op_sel_hi:[1,0]
	s_nop 0
	v_pk_mul_f32 v[68:69], v[58:59], s[32:33] op_sel_hi:[1,0]
	v_exp_f32_e32 v68, v68
	v_exp_f32_e32 v69, v69
	v_pk_mul_f32 v[62:63], v[62:63], v[66:67] op_sel_hi:[1,0]
	v_pk_mul_f32 v[60:61], v[60:61], v[66:67] op_sel_hi:[1,0]
	v_pk_add_f32 v[68:69], v[68:69], 1.0 op_sel_hi:[1,0]
	v_rcp_f32_e32 v68, v68
	v_rcp_f32_e32 v69, v69
	v_pk_mul_f32 v[50:51], v[50:51], v[66:67] op_sel_hi:[1,0]
	v_pk_mul_f32 v[54:55], v[54:55], v[66:67] op_sel_hi:[1,0]
	v_pk_mul_f32 v[64:65], v[64:65], v[66:67] op_sel_hi:[1,0]
	v_pk_mul_f32 v[58:59], v[58:59], v[68:69]
	v_pk_mul_f32 v[56:57], v[56:57], v[66:67] op_sel_hi:[1,0]
	v_pk_mul_f32 v[58:59], v[62:63], v[58:59]
	v_pk_mul_f32 v[62:63], v[60:61], s[32:33] op_sel_hi:[1,0]
	v_exp_f32_e32 v62, v62
	v_exp_f32_e32 v63, v63
	s_nop 0
	v_pk_add_f32 v[62:63], v[62:63], 1.0 op_sel_hi:[1,0]
	v_rcp_f32_e32 v62, v62
	v_rcp_f32_e32 v63, v63
	s_nop 0
	v_pk_mul_f32 v[60:61], v[60:61], v[62:63]
	v_pk_mul_f32 v[62:63], v[50:51], s[32:33] op_sel_hi:[1,0]
	v_exp_f32_e32 v62, v62
	v_exp_f32_e32 v63, v63
	v_pk_mul_f32 v[60:61], v[64:65], v[60:61]
	v_pk_add_f32 v[62:63], v[62:63], 1.0 op_sel_hi:[1,0]
	v_rcp_f32_e32 v62, v62
	v_rcp_f32_e32 v63, v63
	s_nop 0
	v_pk_mul_f32 v[50:51], v[50:51], v[62:63]
	s_nop 0
	v_pk_mul_f32 v[54:55], v[54:55], v[50:51]
	v_pk_mul_f32 v[50:51], v[52:53], v[66:67] op_sel_hi:[1,0]
	s_nop 0
	v_pk_mul_f32 v[52:53], v[50:51], s[32:33] op_sel_hi:[1,0]
	v_exp_f32_e32 v52, v52
	v_exp_f32_e32 v53, v53
	s_nop 0
	v_pk_add_f32 v[52:53], v[52:53], 1.0 op_sel_hi:[1,0]
	v_rcp_f32_e32 v52, v52
	v_rcp_f32_e32 v53, v53
	s_nop 0
	v_pk_mul_f32 v[50:51], v[50:51], v[52:53]
	s_nop 0
	v_pk_mul_f32 v[56:57], v[56:57], v[50:51]
	v_cvt_pk_bf16_f32 v52, v54, v55
	v_mad_i64_i32 v[54:55], s[18:19], v70, s67, v[114:115]
	v_cvt_pk_bf16_f32 v50, v58, v59
	v_cvt_pk_bf16_f32 v51, v60, v61
	v_cvt_pk_bf16_f32 v53, v56, v57
	v_lshl_add_u64 v[54:55], v[54:55], 0, v[116:117]
	global_store_dwordx4 v[54:55], v[50:53], off sc0 sc1
	s_nop 1
	v_mov_b32_e32 v50, v67
	v_pk_mul_f32 v[42:43], v[42:43], v[50:51] op_sel_hi:[1,0]
	s_nop 0
	v_mul_f32_e32 v51, 0xbfb8aa3b, v42
	v_exp_f32_e32 v51, v51
	s_nop 0
	v_add_f32_e32 v51, 1.0, v51
	v_rcp_f32_e32 v52, v51
	v_pk_mul_f32 v[46:47], v[46:47], v[50:51] op_sel_hi:[1,0]
	v_mul_f32_e32 v51, 0xbfb8aa3b, v43
	v_exp_f32_e32 v51, v51
	s_nop 0
	v_add_f32_e32 v51, 1.0, v51
	v_rcp_f32_e32 v53, v51
	v_pk_mul_f32 v[44:45], v[44:45], v[50:51] op_sel_hi:[1,0]
	v_pk_mul_f32 v[34:35], v[34:35], v[50:51] op_sel_hi:[1,0]
	v_pk_mul_f32 v[38:39], v[38:39], v[50:51] op_sel_hi:[1,0]
	v_pk_mul_f32 v[42:43], v[42:43], v[52:53]
	v_pk_mul_f32 v[48:49], v[48:49], v[50:51] op_sel_hi:[1,0]
	v_pk_mul_f32 v[42:43], v[46:47], v[42:43]
	v_pk_mul_f32 v[46:47], v[44:45], s[32:33] op_sel_hi:[1,0]
	v_exp_f32_e32 v46, v46
	v_exp_f32_e32 v47, v47
	v_pk_mul_f32 v[40:41], v[40:41], v[50:51] op_sel_hi:[1,0]
	v_pk_add_f32 v[46:47], v[46:47], 1.0 op_sel_hi:[1,0]
	v_rcp_f32_e32 v46, v46
	v_rcp_f32_e32 v47, v47
	s_nop 0
	v_pk_mul_f32 v[44:45], v[44:45], v[46:47]
	v_pk_mul_f32 v[46:47], v[34:35], s[32:33] op_sel_hi:[1,0]
	v_exp_f32_e32 v46, v46
	v_exp_f32_e32 v47, v47
	v_pk_mul_f32 v[44:45], v[48:49], v[44:45]
	v_pk_add_f32 v[46:47], v[46:47], 1.0 op_sel_hi:[1,0]
	v_rcp_f32_e32 v46, v46
	v_rcp_f32_e32 v47, v47
	s_nop 0
	v_pk_mul_f32 v[34:35], v[34:35], v[46:47]
	s_nop 0
	v_pk_mul_f32 v[38:39], v[38:39], v[34:35]
	v_pk_mul_f32 v[34:35], v[36:37], v[50:51] op_sel_hi:[1,0]
	v_add_u32_e32 v46, 0x90, v130
	v_pk_mul_f32 v[36:37], v[34:35], s[32:33] op_sel_hi:[1,0]
	v_exp_f32_e32 v36, v36
	v_exp_f32_e32 v37, v37
	s_nop 0
	v_pk_add_f32 v[36:37], v[36:37], 1.0 op_sel_hi:[1,0]
	v_rcp_f32_e32 v36, v36
	v_rcp_f32_e32 v37, v37
	s_nop 0
	v_pk_mul_f32 v[34:35], v[34:35], v[36:37]
	s_nop 0
	v_pk_mul_f32 v[40:41], v[40:41], v[34:35]
	v_cvt_pk_bf16_f32 v36, v38, v39
	v_mad_i64_i32 v[38:39], s[18:19], v46, s67, v[114:115]
	v_cvt_pk_bf16_f32 v34, v42, v43
	v_cvt_pk_bf16_f32 v35, v44, v45
	v_cvt_pk_bf16_f32 v37, v40, v41
	v_lshl_add_u64 v[38:39], v[38:39], 0, v[116:117]
	global_store_dwordx4 v[38:39], v[34:37], off sc0 sc1
	ds_read2_b32 v[34:35], v131 offset0:160 offset1:176
	s_waitcnt lgkmcnt(0)
	v_pk_mul_f32 v[26:27], v[26:27], v[34:35] op_sel_hi:[1,0]
	s_nop 0
	v_pk_mul_f32 v[36:37], v[26:27], s[32:33] op_sel_hi:[1,0]
	v_exp_f32_e32 v36, v36
	v_exp_f32_e32 v37, v37
	v_pk_mul_f32 v[30:31], v[30:31], v[34:35] op_sel_hi:[1,0]
	v_pk_mul_f32 v[28:29], v[28:29], v[34:35] op_sel_hi:[1,0]
	v_pk_add_f32 v[36:37], v[36:37], 1.0 op_sel_hi:[1,0]
	v_rcp_f32_e32 v36, v36
	v_rcp_f32_e32 v37, v37
	v_pk_mul_f32 v[18:19], v[18:19], v[34:35] op_sel_hi:[1,0]
	v_pk_mul_f32 v[22:23], v[22:23], v[34:35] op_sel_hi:[1,0]
	v_pk_mul_f32 v[32:33], v[32:33], v[34:35] op_sel_hi:[1,0]
	v_pk_mul_f32 v[26:27], v[26:27], v[36:37]
	v_pk_mul_f32 v[24:25], v[24:25], v[34:35] op_sel_hi:[1,0]
	v_pk_mul_f32 v[26:27], v[30:31], v[26:27]
	v_pk_mul_f32 v[30:31], v[28:29], s[32:33] op_sel_hi:[1,0]
	v_exp_f32_e32 v30, v30
	v_exp_f32_e32 v31, v31
	s_nop 0
	v_pk_add_f32 v[30:31], v[30:31], 1.0 op_sel_hi:[1,0]
	v_rcp_f32_e32 v30, v30
	v_rcp_f32_e32 v31, v31
	s_nop 0
	v_pk_mul_f32 v[28:29], v[28:29], v[30:31]
	v_pk_mul_f32 v[30:31], v[18:19], s[32:33] op_sel_hi:[1,0]
	v_exp_f32_e32 v30, v30
	v_exp_f32_e32 v31, v31
	v_pk_mul_f32 v[28:29], v[32:33], v[28:29]
	v_pk_add_f32 v[30:31], v[30:31], 1.0 op_sel_hi:[1,0]
	v_rcp_f32_e32 v30, v30
	v_rcp_f32_e32 v31, v31
	s_nop 0
	v_pk_mul_f32 v[18:19], v[18:19], v[30:31]
	s_nop 0
	v_pk_mul_f32 v[22:23], v[22:23], v[18:19]
	v_pk_mul_f32 v[18:19], v[20:21], v[34:35] op_sel_hi:[1,0]
	v_add_u32_e32 v30, 0xa0, v130
	v_pk_mul_f32 v[20:21], v[18:19], s[32:33] op_sel_hi:[1,0]
	v_exp_f32_e32 v20, v20
	v_exp_f32_e32 v21, v21
	s_nop 0
	v_pk_add_f32 v[20:21], v[20:21], 1.0 op_sel_hi:[1,0]
	v_rcp_f32_e32 v20, v20
	v_rcp_f32_e32 v21, v21
	s_nop 0
	v_pk_mul_f32 v[18:19], v[18:19], v[20:21]
	s_nop 0
	v_pk_mul_f32 v[24:25], v[24:25], v[18:19]
	v_cvt_pk_bf16_f32 v20, v22, v23
	v_mad_i64_i32 v[22:23], s[18:19], v30, s67, v[114:115]
	v_cvt_pk_bf16_f32 v18, v26, v27
	v_cvt_pk_bf16_f32 v19, v28, v29
	v_cvt_pk_bf16_f32 v21, v24, v25
	v_lshl_add_u64 v[22:23], v[22:23], 0, v[116:117]
	global_store_dwordx4 v[22:23], v[18:21], off sc0 sc1
	s_nop 1
	v_mov_b32_e32 v18, v35
	v_pk_mul_f32 v[10:11], v[10:11], v[18:19] op_sel_hi:[1,0]
	s_nop 0
	v_mul_f32_e32 v19, 0xbfb8aa3b, v10
	v_exp_f32_e32 v19, v19
	s_nop 0
	v_add_f32_e32 v19, 1.0, v19
	v_rcp_f32_e32 v20, v19
	v_pk_mul_f32 v[14:15], v[14:15], v[18:19] op_sel_hi:[1,0]
	v_mul_f32_e32 v19, 0xbfb8aa3b, v11
	v_exp_f32_e32 v19, v19
	s_nop 0
	v_add_f32_e32 v19, 1.0, v19
	v_rcp_f32_e32 v21, v19
	v_pk_mul_f32 v[12:13], v[12:13], v[18:19] op_sel_hi:[1,0]
	v_pk_mul_f32 v[2:3], v[2:3], v[18:19] op_sel_hi:[1,0]
	v_pk_mul_f32 v[6:7], v[6:7], v[18:19] op_sel_hi:[1,0]
	v_pk_mul_f32 v[10:11], v[10:11], v[20:21]
	v_pk_mul_f32 v[16:17], v[16:17], v[18:19] op_sel_hi:[1,0]
	v_pk_mul_f32 v[10:11], v[14:15], v[10:11]
	v_pk_mul_f32 v[14:15], v[12:13], s[32:33] op_sel_hi:[1,0]
	v_exp_f32_e32 v14, v14
	v_exp_f32_e32 v15, v15
	v_pk_mul_f32 v[8:9], v[8:9], v[18:19] op_sel_hi:[1,0]
	v_pk_add_f32 v[14:15], v[14:15], 1.0 op_sel_hi:[1,0]
	v_rcp_f32_e32 v14, v14
	v_rcp_f32_e32 v15, v15
	s_nop 0
	v_pk_mul_f32 v[12:13], v[12:13], v[14:15]
	v_pk_mul_f32 v[14:15], v[2:3], s[32:33] op_sel_hi:[1,0]
	v_exp_f32_e32 v14, v14
	v_exp_f32_e32 v15, v15
	v_pk_mul_f32 v[12:13], v[16:17], v[12:13]
	v_pk_add_f32 v[14:15], v[14:15], 1.0 op_sel_hi:[1,0]
	v_rcp_f32_e32 v14, v14
	v_rcp_f32_e32 v15, v15
	s_nop 0
	v_pk_mul_f32 v[2:3], v[2:3], v[14:15]
	s_nop 0
	v_pk_mul_f32 v[6:7], v[6:7], v[2:3]
	v_pk_mul_f32 v[2:3], v[4:5], v[18:19] op_sel_hi:[1,0]
	v_add_u32_e32 v14, 0xb0, v130
	v_pk_mul_f32 v[4:5], v[2:3], s[32:33] op_sel_hi:[1,0]
	v_exp_f32_e32 v4, v4
	v_exp_f32_e32 v5, v5
	s_nop 0
	v_pk_add_f32 v[4:5], v[4:5], 1.0 op_sel_hi:[1,0]
	v_rcp_f32_e32 v4, v4
	v_rcp_f32_e32 v5, v5
	s_nop 0
	v_pk_mul_f32 v[2:3], v[2:3], v[4:5]
	s_nop 0
	v_pk_mul_f32 v[8:9], v[8:9], v[2:3]
	v_cvt_pk_bf16_f32 v4, v6, v7
	v_mad_i64_i32 v[6:7], s[18:19], v14, s67, v[114:115]
	v_cvt_pk_bf16_f32 v2, v10, v11
	v_cvt_pk_bf16_f32 v3, v12, v13
	v_cvt_pk_bf16_f32 v5, v8, v9
	v_lshl_add_u64 v[6:7], v[6:7], 0, v[116:117]
	global_store_dwordx4 v[6:7], v[2:5], off sc0 sc1
	s_cbranch_vccnz .LBB0_266
	s_andn2_b64 vcc, exec, s[0:1]
	s_cbranch_vccnz .LBB0_265
	s_barrier
	s_branch .LBB0_265

.LBB0_846:
	s_xor_b64 s[18:19], s[80:81], -1
	s_mov_b64 s[16:17], -1
	s_and_b64 vcc, exec, s[18:19]
	s_cbranch_vccz .LBB0_848
	v_lshl_add_u64 v[134:135], v[148:149], 2, s[82:83]
	global_load_dwordx4 v[138:141], v[134:135], off offset:16
	global_load_dwordx4 v[142:145], v[134:135], off
	global_load_dwordx4 v[130:133], v[134:135], off offset:528
	s_nop 0
	global_load_dwordx4 v[134:137], v[134:135], off offset:512
	v_lshl_add_u32 v158, s13, 10, v233
	ds_read2_b32 v[154:155], v158 offset1:16
	v_ashrrev_i32_e32 v147, 31, v146
	v_lshlrev_b64 v[150:151], 10, v[146:147]
	v_lshl_add_u64 v[152:153], v[148:149], 1, s[6:7]
	v_lshl_add_u64 v[150:151], v[152:153], 0, v[150:151]
	s_waitcnt lgkmcnt(0)
	v_mul_f32_e32 v160, v122, v154
	v_mul_f32_e32 v160, 0x3fb8aa3b, v160
	v_exp_f32_e32 v160, v160
	v_mul_f32_e32 v147, v126, v154
	v_mul_f32_e32 v156, v127, v154
	v_mul_f32_e32 v157, v128, v154
	v_add_f32_e32 v160, 1.0, v160
	v_rcp_f32_e32 v160, v160
	v_mul_f32_e32 v159, v129, v154
	v_mul_f32_e32 v147, 0x3fb8aa3b, v147
	v_mul_f32_e32 v156, 0x3fb8aa3b, v156
	v_mul_f32_e32 v157, 0x3fb8aa3b, v157
	v_mul_f32_e32 v159, 0x3fb8aa3b, v159
	v_exp_f32_e32 v147, v147
	v_exp_f32_e32 v156, v156
	v_exp_f32_e32 v157, v157
	v_exp_f32_e32 v159, v159
	v_add_f32_e32 v147, 1.0, v147
	v_pk_add_f32 v[156:157], v[156:157], 1.0 op_sel_hi:[1,0]
	v_add_f32_e32 v159, 1.0, v159
	v_rcp_f32_e32 v147, v147
	v_rcp_f32_e32 v156, v156
	v_rcp_f32_e32 v157, v157
	v_rcp_f32_e32 v159, v159
	s_mov_b32 s0, 0x20000
	s_mov_b64 s[16:17], 0x20000
	s_waitcnt vmcnt(0)
	v_fma_f32 v160, -v138, v160, 1.0
	v_log_f32_e32 v162, v160
	v_mul_f32_e32 v160, v123, v154
	v_mul_f32_e32 v160, 0x3fb8aa3b, v160
	v_exp_f32_e32 v160, v160
	v_fma_f32 v147, -v142, v147, 1.0
	v_fma_f32 v156, -v143, v156, 1.0
	v_fma_f32 v157, -v144, v157, 1.0
	v_add_f32_e32 v160, 1.0, v160
	v_rcp_f32_e32 v160, v160
	v_fma_f32 v159, -v145, v159, 1.0
	v_log_f32_e32 v147, v147
	v_log_f32_e32 v156, v156
	v_fma_f32 v160, -v139, v160, 1.0
	v_log_f32_e32 v163, v160
	v_mul_f32_e32 v160, v124, v154
	v_mul_f32_e32 v160, 0x3fb8aa3b, v160
	v_exp_f32_e32 v160, v160
	v_log_f32_e32 v157, v157
	v_log_f32_e32 v159, v159
	v_cvt_pk_bf16_f32 v162, v162, v163
	v_add_f32_e32 v160, 1.0, v160
	v_rcp_f32_e32 v160, v160
	v_cvt_pk_bf16_f32 v161, v157, v159
	v_mul_f32_e32 v157, v96, v154
	v_mul_f32_e32 v159, v97, v154
	v_fma_f32 v160, -v140, v160, 1.0
	v_log_f32_e32 v164, v160
	v_mul_f32_e32 v160, v125, v154
	v_mul_f32_e32 v160, 0x3fb8aa3b, v160
	v_exp_f32_e32 v160, v160
	v_mul_f32_e32 v157, 0x3fb8aa3b, v157
	v_mul_f32_e32 v159, 0x3fb8aa3b, v159
	v_exp_f32_e32 v157, v157
	v_add_f32_e32 v160, 1.0, v160
	v_rcp_f32_e32 v160, v160
	v_exp_f32_e32 v159, v159
	v_add_f32_e32 v157, 1.0, v157
	v_rcp_f32_e32 v157, v157
	v_fma_f32 v160, -v141, v160, 1.0
	v_log_f32_e32 v165, v160
	v_cvt_pk_bf16_f32 v160, v147, v156
	v_mul_f32_e32 v147, v94, v154
	v_mul_f32_e32 v156, v95, v154
	v_cvt_pk_bf16_f32 v163, v164, v165
	global_store_dwordx4 v[150:151], v[160:163], off
	v_mul_f32_e32 v147, 0x3fb8aa3b, v147
	v_mul_f32_e32 v156, 0x3fb8aa3b, v156
	v_mul_f32_e32 v160, v90, v154
	v_mul_f32_e32 v160, 0x3fb8aa3b, v160
	v_exp_f32_e32 v160, v160
	v_exp_f32_e32 v147, v147
	v_exp_f32_e32 v156, v156
	v_add_f32_e32 v159, 1.0, v159
	v_add_f32_e32 v160, 1.0, v160
	v_rcp_f32_e32 v160, v160
	v_add_f32_e32 v147, 1.0, v147
	v_add_f32_e32 v156, 1.0, v156
	v_rcp_f32_e32 v147, v147
	v_fma_f32 v160, -v130, v160, 1.0
	v_log_f32_e32 v162, v160
	v_mul_f32_e32 v160, v91, v154
	v_mul_f32_e32 v160, 0x3fb8aa3b, v160
	v_exp_f32_e32 v160, v160
	v_rcp_f32_e32 v156, v156
	v_rcp_f32_e32 v159, v159
	v_fma_f32 v147, -v134, v147, 1.0
	v_add_f32_e32 v160, 1.0, v160
	v_rcp_f32_e32 v160, v160
	v_fma_f32 v156, -v135, v156, 1.0
	v_fma_f32 v157, -v136, v157, 1.0
	v_fma_f32 v159, -v137, v159, 1.0
	v_fma_f32 v160, -v131, v160, 1.0
	v_log_f32_e32 v163, v160
	v_mul_f32_e32 v160, v92, v154
	v_mul_f32_e32 v154, v93, v154
	v_mul_f32_e32 v160, 0x3fb8aa3b, v160
	v_mul_f32_e32 v154, 0x3fb8aa3b, v154
	v_exp_f32_e32 v160, v160
	v_exp_f32_e32 v154, v154
	v_log_f32_e32 v147, v147
	v_log_f32_e32 v156, v156
	v_add_f32_e32 v160, 1.0, v160
	v_add_f32_e32 v154, 1.0, v154
	v_rcp_f32_e32 v160, v160
	v_rcp_f32_e32 v154, v154
	v_log_f32_e32 v157, v157
	v_log_f32_e32 v159, v159
	v_fma_f32 v160, -v132, v160, 1.0
	v_fma_f32 v154, -v133, v154, 1.0
	v_log_f32_e32 v164, v160
	v_log_f32_e32 v154, v154
	v_cvt_pk_bf16_f32 v160, v147, v156
	v_cvt_pk_bf16_f32 v161, v157, v159
	v_cvt_pk_bf16_f32 v162, v162, v163
	v_cvt_pk_bf16_f32 v163, v164, v154
	global_store_dwordx4 v[150:151], v[160:163], off offset:256
	v_mul_f32_e32 v147, v118, v155
	v_mul_f32_e32 v154, v119, v155
	v_mul_f32_e32 v160, v121, v155
	v_mul_f32_e32 v160, 0x3fb8aa3b, v160
	v_exp_f32_e32 v160, v160
	v_mul_f32_e32 v159, v120, v155
	v_mul_f32_e32 v147, 0x3fb8aa3b, v147
	v_mul_f32_e32 v154, 0x3fb8aa3b, v154
	v_add_f32_e32 v160, 1.0, v160
	v_rcp_f32_e32 v160, v160
	v_mul_f32_e32 v159, 0x3fb8aa3b, v159
	v_exp_f32_e32 v147, v147
	v_exp_f32_e32 v154, v154
	v_fma_f32 v160, -v145, v160, 1.0
	v_log_f32_e32 v161, v160
	v_mul_f32_e32 v160, v114, v155
	v_mul_f32_e32 v160, 0x3fb8aa3b, v160
	v_exp_f32_e32 v160, v160
	v_exp_f32_e32 v159, v159
	v_add_f32_e32 v147, 1.0, v147
	v_add_f32_e32 v154, 1.0, v154
	v_add_f32_e32 v160, 1.0, v160
	v_rcp_f32_e32 v160, v160
	v_add_f32_e32 v159, 1.0, v159
	v_rcp_f32_e32 v147, v147
	v_rcp_f32_e32 v154, v154
	v_fma_f32 v160, -v138, v160, 1.0
	v_log_f32_e32 v162, v160
	v_mul_f32_e32 v160, v115, v155
	v_mul_f32_e32 v160, 0x3fb8aa3b, v160
	v_exp_f32_e32 v160, v160
	v_rcp_f32_e32 v159, v159
	v_fma_f32 v147, -v142, v147, 1.0
	v_fma_f32 v154, -v143, v154, 1.0
	v_add_f32_e32 v160, 1.0, v160
	v_rcp_f32_e32 v160, v160
	v_fma_f32 v159, -v144, v159, 1.0
	v_log_f32_e32 v147, v147
	v_log_f32_e32 v154, v154
	v_fma_f32 v160, -v139, v160, 1.0
	v_log_f32_e32 v163, v160
	v_mul_f32_e32 v160, v116, v155
	v_mul_f32_e32 v160, 0x3fb8aa3b, v160
	v_exp_f32_e32 v160, v160
	v_log_f32_e32 v159, v159
	v_or_b32_e32 v156, 16, v146
	v_ashrrev_i32_e32 v157, 31, v156
	v_add_f32_e32 v160, 1.0, v160
	v_rcp_f32_e32 v160, v160
	v_lshlrev_b64 v[156:157], 10, v[156:157]
	v_lshl_add_u64 v[156:157], v[152:153], 0, v[156:157]
	v_cvt_pk_bf16_f32 v161, v159, v161
	v_fma_f32 v160, -v140, v160, 1.0
	v_log_f32_e32 v164, v160
	v_mul_f32_e32 v160, v117, v155
	v_mul_f32_e32 v160, 0x3fb8aa3b, v160
	v_exp_f32_e32 v160, v160
	v_cvt_pk_bf16_f32 v162, v162, v163
	v_mul_f32_e32 v159, v88, v155
	v_mul_f32_e32 v159, 0x3fb8aa3b, v159
	v_add_f32_e32 v160, 1.0, v160
	v_rcp_f32_e32 v160, v160
	v_exp_f32_e32 v159, v159
	v_fma_f32 v160, -v141, v160, 1.0
	v_log_f32_e32 v165, v160
	v_cvt_pk_bf16_f32 v160, v147, v154
	v_mul_f32_e32 v147, v86, v155
	v_mul_f32_e32 v154, v87, v155
	v_cvt_pk_bf16_f32 v163, v164, v165
	global_store_dwordx4 v[156:157], v[160:163], off
	v_mul_f32_e32 v147, 0x3fb8aa3b, v147
	v_mul_f32_e32 v154, 0x3fb8aa3b, v154
	v_mul_f32_e32 v160, v89, v155
	v_mul_f32_e32 v160, 0x3fb8aa3b, v160
	v_exp_f32_e32 v160, v160
	v_exp_f32_e32 v147, v147
	v_exp_f32_e32 v154, v154
	v_add_f32_e32 v159, 1.0, v159
	v_add_f32_e32 v160, 1.0, v160
	v_rcp_f32_e32 v160, v160
	v_add_f32_e32 v147, 1.0, v147
	v_add_f32_e32 v154, 1.0, v154
	v_rcp_f32_e32 v147, v147
	v_fma_f32 v160, -v137, v160, 1.0
	v_log_f32_e32 v161, v160
	v_mul_f32_e32 v160, v82, v155
	v_mul_f32_e32 v160, 0x3fb8aa3b, v160
	v_exp_f32_e32 v160, v160
	v_rcp_f32_e32 v154, v154
	v_fma_f32 v147, -v134, v147, 1.0
	v_rcp_f32_e32 v159, v159
	v_add_f32_e32 v160, 1.0, v160
	v_rcp_f32_e32 v160, v160
	v_fma_f32 v154, -v135, v154, 1.0
	v_log_f32_e32 v147, v147
	v_log_f32_e32 v154, v154
	v_fma_f32 v160, -v130, v160, 1.0
	v_log_f32_e32 v162, v160
	v_mul_f32_e32 v160, v83, v155
	v_mul_f32_e32 v160, 0x3fb8aa3b, v160
	v_exp_f32_e32 v160, v160
	v_fma_f32 v159, -v136, v159, 1.0
	v_log_f32_e32 v159, v159
	v_add_f32_e32 v160, 1.0, v160
	v_rcp_f32_e32 v160, v160
	v_cvt_pk_bf16_f32 v161, v159, v161
	v_fma_f32 v160, -v131, v160, 1.0
	v_log_f32_e32 v163, v160
	v_mul_f32_e32 v160, v84, v155
	v_mul_f32_e32 v155, v85, v155
	v_mul_f32_e32 v160, 0x3fb8aa3b, v160
	v_mul_f32_e32 v155, 0x3fb8aa3b, v155
	v_exp_f32_e32 v160, v160
	v_exp_f32_e32 v155, v155
	v_cvt_pk_bf16_f32 v162, v162, v163
	v_add_f32_e32 v160, 1.0, v160
	v_add_f32_e32 v155, 1.0, v155
	v_rcp_f32_e32 v160, v160
	v_rcp_f32_e32 v155, v155
	v_fma_f32 v160, -v132, v160, 1.0
	v_fma_f32 v155, -v133, v155, 1.0
	v_log_f32_e32 v164, v160
	v_log_f32_e32 v155, v155
	v_cvt_pk_bf16_f32 v160, v147, v154
	v_cvt_pk_bf16_f32 v163, v164, v155
	ds_read2_b32 v[154:155], v158 offset0:32 offset1:48
	global_store_dwordx4 v[156:157], v[160:163], off offset:256
	v_or_b32_e32 v156, 32, v146
	v_ashrrev_i32_e32 v157, 31, v156
	v_lshlrev_b64 v[156:157], 10, v[156:157]
	s_waitcnt lgkmcnt(0)
	v_mul_f32_e32 v160, v112, v154
	v_mul_f32_e32 v160, 0x3fb8aa3b, v160
	v_exp_f32_e32 v160, v160
	v_mul_f32_e32 v147, v110, v154
	v_mul_f32_e32 v159, v111, v154
	v_mul_f32_e32 v147, 0x3fb8aa3b, v147
	v_add_f32_e32 v160, 1.0, v160
	v_rcp_f32_e32 v160, v160
	v_mul_f32_e32 v159, 0x3fb8aa3b, v159
	v_exp_f32_e32 v147, v147
	v_exp_f32_e32 v159, v159
	v_fma_f32 v160, -v144, v160, 1.0
	v_log_f32_e32 v161, v160
	v_mul_f32_e32 v160, v113, v154
	v_mul_f32_e32 v160, 0x3fb8aa3b, v160
	v_exp_f32_e32 v160, v160
	v_add_f32_e32 v147, 1.0, v147
	v_add_f32_e32 v159, 1.0, v159
	v_rcp_f32_e32 v147, v147
	v_add_f32_e32 v160, 1.0, v160
	v_rcp_f32_e32 v160, v160
	v_rcp_f32_e32 v159, v159
	v_fma_f32 v147, -v142, v147, 1.0
	v_log_f32_e32 v147, v147
	v_fma_f32 v160, -v145, v160, 1.0
	v_log_f32_e32 v162, v160
	v_mul_f32_e32 v160, v106, v154
	v_mul_f32_e32 v160, 0x3fb8aa3b, v160
	v_exp_f32_e32 v160, v160
	v_fma_f32 v159, -v143, v159, 1.0
	v_log_f32_e32 v159, v159
	v_lshl_add_u64 v[156:157], v[152:153], 0, v[156:157]
	v_add_f32_e32 v160, 1.0, v160
	v_rcp_f32_e32 v160, v160
	v_cvt_pk_bf16_f32 v161, v161, v162
	v_fma_f32 v160, -v138, v160, 1.0
	v_log_f32_e32 v163, v160
	v_mul_f32_e32 v160, v107, v154
	v_mul_f32_e32 v160, 0x3fb8aa3b, v160
	v_exp_f32_e32 v160, v160
	s_nop 0
	v_add_f32_e32 v160, 1.0, v160
	v_rcp_f32_e32 v160, v160
	s_nop 0
	v_fma_f32 v160, -v139, v160, 1.0
	v_log_f32_e32 v164, v160
	v_mul_f32_e32 v160, v108, v154
	v_mul_f32_e32 v160, 0x3fb8aa3b, v160
	v_exp_f32_e32 v160, v160
	v_cvt_pk_bf16_f32 v162, v163, v164
	v_add_f32_e32 v160, 1.0, v160
	v_rcp_f32_e32 v160, v160
	s_nop 0
	v_fma_f32 v160, -v140, v160, 1.0
	v_log_f32_e32 v165, v160
	v_mul_f32_e32 v160, v109, v154
	v_mul_f32_e32 v160, 0x3fb8aa3b, v160
	v_exp_f32_e32 v160, v160
	s_nop 0
	v_add_f32_e32 v160, 1.0, v160
	v_rcp_f32_e32 v160, v160
	s_nop 0
	v_fma_f32 v160, -v141, v160, 1.0
	v_log_f32_e32 v166, v160
	v_cvt_pk_bf16_f32 v160, v147, v159
	v_mul_f32_e32 v147, v78, v154
	v_mul_f32_e32 v159, v79, v154
	v_cvt_pk_bf16_f32 v163, v165, v166
	global_store_dwordx4 v[156:157], v[160:163], off
	v_mul_f32_e32 v147, 0x3fb8aa3b, v147
	v_mul_f32_e32 v159, 0x3fb8aa3b, v159
	v_mul_f32_e32 v160, v80, v154
	v_mul_f32_e32 v160, 0x3fb8aa3b, v160
	v_exp_f32_e32 v160, v160
	v_exp_f32_e32 v147, v147
	v_exp_f32_e32 v159, v159
	v_add_f32_e32 v160, 1.0, v160
	v_rcp_f32_e32 v160, v160
	v_add_f32_e32 v147, 1.0, v147
	v_add_f32_e32 v159, 1.0, v159
	v_rcp_f32_e32 v147, v147
	v_fma_f32 v160, -v136, v160, 1.0
	v_log_f32_e32 v161, v160
	v_mul_f32_e32 v160, v81, v154
	v_mul_f32_e32 v160, 0x3fb8aa3b, v160
	v_exp_f32_e32 v160, v160
	v_rcp_f32_e32 v159, v159
	v_fma_f32 v147, -v134, v147, 1.0
	v_log_f32_e32 v147, v147
	v_add_f32_e32 v160, 1.0, v160
	v_rcp_f32_e32 v160, v160
	v_fma_f32 v159, -v135, v159, 1.0
	v_log_f32_e32 v159, v159
	v_fma_f32 v160, -v137, v160, 1.0
	v_log_f32_e32 v162, v160
	v_mul_f32_e32 v160, v74, v154
	v_mul_f32_e32 v160, 0x3fb8aa3b, v160
	v_exp_f32_e32 v160, v160
	v_cvt_pk_bf16_f32 v161, v161, v162
	v_add_f32_e32 v160, 1.0, v160
	v_rcp_f32_e32 v160, v160
	s_nop 0
	v_fma_f32 v160, -v130, v160, 1.0
	v_log_f32_e32 v163, v160
	v_mul_f32_e32 v160, v75, v154
	v_mul_f32_e32 v160, 0x3fb8aa3b, v160
	v_exp_f32_e32 v160, v160
	s_nop 0
	v_add_f32_e32 v160, 1.0, v160
	v_rcp_f32_e32 v160, v160
	s_nop 0
	v_fma_f32 v160, -v131, v160, 1.0
	v_log_f32_e32 v164, v160
	v_mul_f32_e32 v160, v76, v154
	v_mul_f32_e32 v154, v77, v154
	v_mul_f32_e32 v160, 0x3fb8aa3b, v160
	v_mul_f32_e32 v154, 0x3fb8aa3b, v154
	v_exp_f32_e32 v160, v160
	v_exp_f32_e32 v154, v154
	v_cvt_pk_bf16_f32 v162, v163, v164
	v_add_f32_e32 v160, 1.0, v160
	v_add_f32_e32 v154, 1.0, v154
	v_rcp_f32_e32 v160, v160
	v_rcp_f32_e32 v154, v154
	v_fma_f32 v160, -v132, v160, 1.0
	v_fma_f32 v154, -v133, v154, 1.0
	v_log_f32_e32 v165, v160
	v_log_f32_e32 v154, v154
	v_cvt_pk_bf16_f32 v160, v147, v159
	v_mul_f32_e32 v147, v102, v155
	v_mul_f32_e32 v159, v98, v155
	v_cvt_pk_bf16_f32 v163, v165, v154
	global_store_dwordx4 v[156:157], v[160:163], off offset:256
	v_or_b32_e32 v156, 48, v146
	v_ashrrev_i32_e32 v157, 31, v156
	v_mul_f32_e32 v160, v99, v155
	v_mul_f32_e32 v160, 0x3fb8aa3b, v160
	v_exp_f32_e32 v160, v160
	v_lshlrev_b64 v[156:157], 10, v[156:157]
	v_lshl_add_u64 v[152:153], v[152:153], 0, v[156:157]
	v_mul_f32_e32 v154, v103, v155
	v_add_f32_e32 v160, 1.0, v160
	v_rcp_f32_e32 v160, v160
	v_mul_f32_e32 v156, v104, v155
	v_mul_f32_e32 v157, v105, v155
	v_mul_f32_e32 v147, 0x3fb8aa3b, v147
	v_fma_f32 v160, -v139, v160, 1.0
	v_log_f32_e32 v162, v160
	v_mul_f32_e32 v160, v100, v155
	v_mul_f32_e32 v160, 0x3fb8aa3b, v160
	v_exp_f32_e32 v160, v160
	v_mul_f32_e32 v154, 0x3fb8aa3b, v154
	v_mul_f32_e32 v156, 0x3fb8aa3b, v156
	v_mul_f32_e32 v157, 0x3fb8aa3b, v157
	v_add_f32_e32 v160, 1.0, v160
	v_rcp_f32_e32 v160, v160
	v_mul_f32_e32 v159, 0x3fb8aa3b, v159
	v_exp_f32_e32 v147, v147
	v_exp_f32_e32 v154, v154
	v_fma_f32 v160, -v140, v160, 1.0
	v_log_f32_e32 v163, v160
	v_mul_f32_e32 v160, v101, v155
	v_mul_f32_e32 v160, 0x3fb8aa3b, v160
	v_exp_f32_e32 v156, v156
	v_exp_f32_e32 v157, v157
	v_exp_f32_e32 v159, v159
	v_exp_f32_e32 v160, v160
	v_add_f32_e32 v147, 1.0, v147
	v_add_f32_e32 v154, 1.0, v154
	v_pk_add_f32 v[156:157], v[156:157], 1.0 op_sel_hi:[1,0]
	v_add_f32_e32 v159, 1.0, v159
	v_add_f32_e32 v160, 1.0, v160
	v_rcp_f32_e32 v147, v147
	v_rcp_f32_e32 v154, v154
	v_rcp_f32_e32 v156, v156
	v_rcp_f32_e32 v157, v157
	v_rcp_f32_e32 v159, v159
	v_rcp_f32_e32 v160, v160
	v_fma_f32 v147, -v142, v147, 1.0
	v_fma_f32 v154, -v143, v154, 1.0
	v_fma_f32 v156, -v144, v156, 1.0
	v_fma_f32 v157, -v145, v157, 1.0
	v_fma_f32 v159, -v138, v159, 1.0
	v_fma_f32 v160, -v141, v160, 1.0
	v_log_f32_e32 v147, v147
	v_log_f32_e32 v154, v154
	v_log_f32_e32 v156, v156
	v_log_f32_e32 v157, v157
	v_log_f32_e32 v159, v159
	v_log_f32_e32 v164, v160
	v_cvt_pk_bf16_f32 v160, v147, v154
	v_cvt_pk_bf16_f32 v161, v156, v157
	v_cvt_pk_bf16_f32 v162, v159, v162
	v_cvt_pk_bf16_f32 v163, v163, v164
	global_store_dwordx4 v[152:153], v[160:163], off
	v_mul_f32_e32 v147, v70, v155
	v_mul_f32_e32 v154, v71, v155
	v_mul_f32_e32 v156, v72, v155
	v_mul_f32_e32 v157, v73, v155
	v_mul_f32_e32 v159, v58, v155
	v_mul_f32_e32 v160, v59, v155
	v_mul_f32_e32 v161, v60, v155
	v_mul_f32_e32 v155, v61, v155
	v_mul_f32_e32 v147, 0x3fb8aa3b, v147
	v_mul_f32_e32 v154, 0x3fb8aa3b, v154
	v_mul_f32_e32 v156, 0x3fb8aa3b, v156
	v_mul_f32_e32 v157, 0x3fb8aa3b, v157
	v_mul_f32_e32 v159, 0x3fb8aa3b, v159
	v_mul_f32_e32 v160, 0x3fb8aa3b, v160
	v_mul_f32_e32 v161, 0x3fb8aa3b, v161
	v_mul_f32_e32 v155, 0x3fb8aa3b, v155
	v_exp_f32_e32 v147, v147
	v_exp_f32_e32 v154, v154
	v_exp_f32_e32 v156, v156
	v_exp_f32_e32 v157, v157
	v_exp_f32_e32 v159, v159
	v_exp_f32_e32 v160, v160
	v_exp_f32_e32 v161, v161
	v_exp_f32_e32 v155, v155
	v_add_f32_e32 v147, 1.0, v147
	v_add_f32_e32 v154, 1.0, v154
	v_pk_add_f32 v[156:157], v[156:157], 1.0 op_sel_hi:[1,0]
	v_add_f32_e32 v159, 1.0, v159
	v_pk_add_f32 v[160:161], v[160:161], 1.0 op_sel_hi:[1,0]
	v_add_f32_e32 v155, 1.0, v155
	v_rcp_f32_e32 v147, v147
	v_rcp_f32_e32 v154, v154
	v_rcp_f32_e32 v156, v156
	v_rcp_f32_e32 v157, v157
	v_rcp_f32_e32 v159, v159
	v_rcp_f32_e32 v160, v160
	v_rcp_f32_e32 v161, v161
	v_rcp_f32_e32 v155, v155
	v_fma_f32 v147, -v134, v147, 1.0
	v_fma_f32 v154, -v135, v154, 1.0
	v_fma_f32 v156, -v136, v156, 1.0
	v_fma_f32 v157, -v137, v157, 1.0
	v_fma_f32 v159, -v130, v159, 1.0
	v_fma_f32 v160, -v131, v160, 1.0
	v_fma_f32 v161, -v132, v161, 1.0
	v_fma_f32 v155, -v133, v155, 1.0
	v_log_f32_e32 v147, v147
	v_log_f32_e32 v154, v154
	v_log_f32_e32 v156, v156
	v_log_f32_e32 v157, v157
	v_log_f32_e32 v159, v159
	v_log_f32_e32 v160, v160
	v_log_f32_e32 v161, v161
	v_log_f32_e32 v162, v155
	v_cvt_pk_bf16_f32 v154, v147, v154
	v_cvt_pk_bf16_f32 v155, v156, v157
	v_cvt_pk_bf16_f32 v156, v159, v160
	v_cvt_pk_bf16_f32 v157, v161, v162
	global_store_dwordx4 v[152:153], v[154:157], off offset:256
	ds_read2_b32 v[152:153], v158 offset0:128 offset1:144
	s_waitcnt lgkmcnt(0)
	v_mul_f32_e32 v160, v62, v152
	v_mul_f32_e32 v160, 0x3fb8aa3b, v160
	v_exp_f32_e32 v160, v160
	v_mul_f32_e32 v147, v66, v152
	v_mul_f32_e32 v156, v67, v152
	v_mul_f32_e32 v147, 0x3fb8aa3b, v147
	v_add_f32_e32 v160, 1.0, v160
	v_rcp_f32_e32 v160, v160
	v_mul_f32_e32 v156, 0x3fb8aa3b, v156
	v_mul_f32_e32 v157, v68, v152
	v_mul_f32_e32 v159, v69, v152
	v_fma_f32 v160, -v138, v160, 1.0
	v_log_f32_e32 v162, v160
	v_mul_f32_e32 v160, v63, v152
	v_mul_f32_e32 v160, 0x3fb8aa3b, v160
	v_exp_f32_e32 v160, v160
	v_exp_f32_e32 v147, v147
	v_exp_f32_e32 v156, v156
	v_mul_f32_e32 v157, 0x3fb8aa3b, v157
	v_add_f32_e32 v160, 1.0, v160
	v_rcp_f32_e32 v160, v160
	v_mul_f32_e32 v159, 0x3fb8aa3b, v159
	v_exp_f32_e32 v157, v157
	v_exp_f32_e32 v159, v159
	v_fma_f32 v160, -v139, v160, 1.0
	v_log_f32_e32 v163, v160
	v_mul_f32_e32 v160, v64, v152
	v_mul_f32_e32 v160, 0x3fb8aa3b, v160
	v_exp_f32_e32 v160, v160
	v_add_f32_e32 v147, 1.0, v147
	v_add_f32_e32 v156, 1.0, v156
	v_rcp_f32_e32 v147, v147
	v_add_f32_e32 v160, 1.0, v160
	v_rcp_f32_e32 v160, v160
	v_rcp_f32_e32 v156, v156
	v_add_f32_e32 v157, 1.0, v157
	v_add_f32_e32 v159, 1.0, v159
	v_fma_f32 v160, -v140, v160, 1.0
	v_log_f32_e32 v164, v160
	v_mul_f32_e32 v160, v65, v152
	v_mul_f32_e32 v160, 0x3fb8aa3b, v160
	v_exp_f32_e32 v160, v160
	v_rcp_f32_e32 v157, v157
	v_rcp_f32_e32 v159, v159
	v_fma_f32 v147, -v142, v147, 1.0
	v_add_f32_e32 v160, 1.0, v160
	v_rcp_f32_e32 v160, v160
	v_fma_f32 v156, -v143, v156, 1.0
	v_log_f32_e32 v147, v147
	v_log_f32_e32 v156, v156
	v_fma_f32 v157, -v144, v157, 1.0
	v_fma_f32 v159, -v145, v159, 1.0
	v_fma_f32 v160, -v141, v160, 1.0
	v_log_f32_e32 v157, v157
	v_log_f32_e32 v159, v159
	v_log_f32_e32 v165, v160
	v_cvt_pk_bf16_f32 v160, v147, v156
	v_add_co_u32_e32 v156, vcc, s0, v150
	v_cvt_pk_bf16_f32 v161, v157, v159
	v_cvt_pk_bf16_f32 v162, v162, v163
	v_cvt_pk_bf16_f32 v163, v164, v165
	v_addc_co_u32_e32 v157, vcc, 0, v151, vcc
	global_store_dwordx4 v[156:157], v[160:163], off
	v_mul_f32_e32 v147, v30, v152
	v_mul_f32_e32 v156, v31, v152
	v_mul_f32_e32 v160, v26, v152
	v_mul_f32_e32 v160, 0x3fb8aa3b, v160
	v_exp_f32_e32 v160, v160
	v_mul_f32_e32 v157, v32, v152
	v_mul_f32_e32 v159, v33, v152
	v_mul_f32_e32 v147, 0x3fb8aa3b, v147
	v_add_f32_e32 v160, 1.0, v160
	v_rcp_f32_e32 v160, v160
	v_mul_f32_e32 v156, 0x3fb8aa3b, v156
	v_mul_f32_e32 v157, 0x3fb8aa3b, v157
	v_mul_f32_e32 v159, 0x3fb8aa3b, v159
	v_fma_f32 v160, -v130, v160, 1.0
	v_log_f32_e32 v162, v160
	v_mul_f32_e32 v160, v27, v152
	v_mul_f32_e32 v160, 0x3fb8aa3b, v160
	v_exp_f32_e32 v160, v160
	v_exp_f32_e32 v147, v147
	v_exp_f32_e32 v156, v156
	v_exp_f32_e32 v157, v157
	v_add_f32_e32 v160, 1.0, v160
	v_rcp_f32_e32 v160, v160
	v_exp_f32_e32 v159, v159
	v_add_f32_e32 v147, 1.0, v147
	v_add_f32_e32 v156, 1.0, v156
	v_fma_f32 v160, -v131, v160, 1.0
	v_log_f32_e32 v163, v160
	v_mul_f32_e32 v160, v28, v152
	v_mul_f32_e32 v152, v29, v152
	v_mul_f32_e32 v160, 0x3fb8aa3b, v160
	v_mul_f32_e32 v152, 0x3fb8aa3b, v152
	v_exp_f32_e32 v160, v160
	v_exp_f32_e32 v152, v152
	v_add_f32_e32 v157, 1.0, v157
	v_add_f32_e32 v159, 1.0, v159
	v_add_f32_e32 v160, 1.0, v160
	v_add_f32_e32 v152, 1.0, v152
	v_rcp_f32_e32 v147, v147
	v_rcp_f32_e32 v156, v156
	v_rcp_f32_e32 v157, v157
	v_rcp_f32_e32 v159, v159
	v_rcp_f32_e32 v160, v160
	v_rcp_f32_e32 v152, v152
	v_fma_f32 v147, -v134, v147, 1.0
	v_fma_f32 v156, -v135, v156, 1.0
	v_fma_f32 v157, -v136, v157, 1.0
	v_fma_f32 v159, -v137, v159, 1.0
	v_fma_f32 v160, -v132, v160, 1.0
	v_fma_f32 v152, -v133, v152, 1.0
	v_log_f32_e32 v147, v147
	v_log_f32_e32 v156, v156
	v_log_f32_e32 v157, v157
	v_log_f32_e32 v159, v159
	v_log_f32_e32 v164, v160
	v_log_f32_e32 v152, v152
	v_lshl_add_u64 v[154:155], v[150:151], 0, s[16:17]
	v_cvt_pk_bf16_f32 v160, v147, v156
	v_cvt_pk_bf16_f32 v161, v157, v159
	v_cvt_pk_bf16_f32 v162, v162, v163
	v_cvt_pk_bf16_f32 v163, v164, v152
	global_store_dwordx4 v[154:155], v[160:163], off offset:256
	v_mul_f32_e32 v156, v56, v153
	v_mul_f32_e32 v157, v57, v153
	v_mul_f32_e32 v160, v51, v153
	v_mul_f32_e32 v160, 0x3fb8aa3b, v160
	v_exp_f32_e32 v160, v160
	v_mul_f32_e32 v147, v54, v153
	v_mul_f32_e32 v152, v55, v153
	v_mul_f32_e32 v156, 0x3fb8aa3b, v156
	v_add_f32_e32 v160, 1.0, v160
	v_rcp_f32_e32 v160, v160
	v_mul_f32_e32 v157, 0x3fb8aa3b, v157
	v_mul_f32_e32 v159, v50, v153
	v_mul_f32_e32 v147, 0x3fb8aa3b, v147
	v_fma_f32 v160, -v139, v160, 1.0
	v_log_f32_e32 v162, v160
	v_mul_f32_e32 v160, v52, v153
	v_mul_f32_e32 v160, 0x3fb8aa3b, v160
	v_exp_f32_e32 v160, v160
	v_mul_f32_e32 v152, 0x3fb8aa3b, v152
	v_exp_f32_e32 v156, v156
	v_exp_f32_e32 v157, v157
	v_add_f32_e32 v160, 1.0, v160
	v_rcp_f32_e32 v160, v160
	v_mul_f32_e32 v159, 0x3fb8aa3b, v159
	v_exp_f32_e32 v147, v147
	v_exp_f32_e32 v152, v152
	v_fma_f32 v160, -v140, v160, 1.0
	v_log_f32_e32 v163, v160
	v_mul_f32_e32 v160, v53, v153
	v_mul_f32_e32 v160, 0x3fb8aa3b, v160
	v_exp_f32_e32 v159, v159
	v_exp_f32_e32 v160, v160
	v_pk_add_f32 v[156:157], v[156:157], 1.0 op_sel_hi:[1,0]
	v_add_f32_e32 v147, 1.0, v147
	v_add_f32_e32 v152, 1.0, v152
	v_rcp_f32_e32 v156, v156
	v_rcp_f32_e32 v157, v157
	v_add_f32_e32 v159, 1.0, v159
	v_add_f32_e32 v160, 1.0, v160
	v_rcp_f32_e32 v147, v147
	v_rcp_f32_e32 v152, v152
	v_rcp_f32_e32 v159, v159
	v_rcp_f32_e32 v160, v160
	v_fma_f32 v156, -v144, v156, 1.0
	v_fma_f32 v157, -v145, v157, 1.0
	v_fma_f32 v147, -v142, v147, 1.0
	v_fma_f32 v152, -v143, v152, 1.0
	v_log_f32_e32 v156, v156
	v_log_f32_e32 v157, v157
	v_fma_f32 v159, -v138, v159, 1.0
	v_fma_f32 v160, -v141, v160, 1.0
	v_log_f32_e32 v147, v147
	v_log_f32_e32 v152, v152
	v_log_f32_e32 v159, v159
	v_log_f32_e32 v164, v160
	s_mov_b32 s0, 0x24000
	v_cvt_pk_bf16_f32 v161, v156, v157
	v_add_co_u32_e32 v156, vcc, s0, v150
	v_cvt_pk_bf16_f32 v160, v147, v152
	v_cvt_pk_bf16_f32 v162, v159, v162
	v_cvt_pk_bf16_f32 v163, v163, v164
	v_addc_co_u32_e32 v157, vcc, 0, v151, vcc
	global_store_dwordx4 v[156:157], v[160:163], off
	v_mul_f32_e32 v147, v22, v153
	v_mul_f32_e32 v152, v23, v153
	v_mul_f32_e32 v160, v19, v153
	v_mul_f32_e32 v160, 0x3fb8aa3b, v160
	v_exp_f32_e32 v160, v160
	v_mul_f32_e32 v156, v24, v153
	v_mul_f32_e32 v157, v25, v153
	v_mul_f32_e32 v159, v18, v153
	v_add_f32_e32 v160, 1.0, v160
	v_rcp_f32_e32 v160, v160
	v_mul_f32_e32 v147, 0x3fb8aa3b, v147
	v_mul_f32_e32 v152, 0x3fb8aa3b, v152
	v_exp_f32_e32 v147, v147
	v_fma_f32 v160, -v131, v160, 1.0
	v_log_f32_e32 v162, v160
	v_mul_f32_e32 v160, v20, v153
	v_mul_f32_e32 v153, v21, v153
	v_mul_f32_e32 v160, 0x3fb8aa3b, v160
	v_mul_f32_e32 v153, 0x3fb8aa3b, v153
	v_exp_f32_e32 v152, v152
	v_exp_f32_e32 v160, v160
	v_exp_f32_e32 v153, v153
	v_mul_f32_e32 v156, 0x3fb8aa3b, v156
	v_mul_f32_e32 v157, 0x3fb8aa3b, v157
	v_mul_f32_e32 v159, 0x3fb8aa3b, v159
	v_add_f32_e32 v147, 1.0, v147
	v_add_f32_e32 v152, 1.0, v152
	v_exp_f32_e32 v156, v156
	v_exp_f32_e32 v157, v157
	v_exp_f32_e32 v159, v159
	v_add_f32_e32 v160, 1.0, v160
	v_add_f32_e32 v153, 1.0, v153
	v_rcp_f32_e32 v147, v147
	v_rcp_f32_e32 v152, v152
	v_rcp_f32_e32 v160, v160
	v_rcp_f32_e32 v153, v153
	v_pk_add_f32 v[156:157], v[156:157], 1.0 op_sel_hi:[1,0]
	v_add_f32_e32 v159, 1.0, v159
	v_fma_f32 v147, -v134, v147, 1.0
	v_fma_f32 v152, -v135, v152, 1.0
	v_rcp_f32_e32 v156, v156
	v_rcp_f32_e32 v157, v157
	v_rcp_f32_e32 v159, v159
	v_fma_f32 v160, -v132, v160, 1.0
	v_fma_f32 v153, -v133, v153, 1.0
	v_log_f32_e32 v147, v147
	v_log_f32_e32 v152, v152
	v_log_f32_e32 v163, v160
	v_log_f32_e32 v153, v153
	v_fma_f32 v156, -v136, v156, 1.0
	v_fma_f32 v157, -v137, v157, 1.0
	v_fma_f32 v159, -v130, v159, 1.0
	v_log_f32_e32 v156, v156
	v_log_f32_e32 v157, v157
	v_log_f32_e32 v159, v159
	v_cvt_pk_bf16_f32 v160, v147, v152
	v_cvt_pk_bf16_f32 v163, v163, v153
	ds_read2_b32 v[152:153], v158 offset0:160 offset1:176
	s_mov_b64 s[16:17], 0x24000
	v_lshl_add_u64 v[154:155], v[150:151], 0, s[16:17]
	v_cvt_pk_bf16_f32 v161, v156, v157
	v_cvt_pk_bf16_f32 v162, v159, v162
	global_store_dwordx4 v[154:155], v[160:163], off offset:256
	s_waitcnt lgkmcnt(0)
	v_mul_f32_e32 v157, v48, v152
	v_mul_f32_e32 v158, v49, v152
	v_mul_f32_e32 v159, v42, v152
	v_mul_f32_e32 v160, v43, v152
	v_mul_f32_e32 v147, v46, v152
	v_mul_f32_e32 v156, v47, v152
	v_mul_f32_e32 v157, 0x3fb8aa3b, v157
	v_mul_f32_e32 v158, 0x3fb8aa3b, v158
	v_mul_f32_e32 v159, 0x3fb8aa3b, v159
	v_mul_f32_e32 v160, 0x3fb8aa3b, v160
	v_mul_f32_e32 v161, v44, v152
	v_mul_f32_e32 v162, v45, v152
	v_mul_f32_e32 v147, 0x3fb8aa3b, v147
	v_mul_f32_e32 v156, 0x3fb8aa3b, v156
	v_exp_f32_e32 v157, v157
	v_exp_f32_e32 v158, v158
	v_exp_f32_e32 v159, v159
	v_exp_f32_e32 v160, v160
	v_mul_f32_e32 v161, 0x3fb8aa3b, v161
	v_mul_f32_e32 v162, 0x3fb8aa3b, v162
	v_exp_f32_e32 v147, v147
	v_exp_f32_e32 v156, v156
	v_exp_f32_e32 v161, v161
	v_exp_f32_e32 v162, v162
	v_add_f32_e32 v157, 1.0, v157
	v_pk_add_f32 v[158:159], v[158:159], 1.0 op_sel_hi:[1,0]
	v_add_f32_e32 v160, 1.0, v160
	v_add_f32_e32 v147, 1.0, v147
	v_add_f32_e32 v156, 1.0, v156
	v_rcp_f32_e32 v157, v157
	v_rcp_f32_e32 v158, v158
	v_rcp_f32_e32 v159, v159
	v_rcp_f32_e32 v160, v160
	v_add_f32_e32 v161, 1.0, v161
	v_add_f32_e32 v162, 1.0, v162
	v_rcp_f32_e32 v147, v147
	v_rcp_f32_e32 v156, v156
	v_rcp_f32_e32 v161, v161
	v_rcp_f32_e32 v162, v162
	v_fma_f32 v157, -v144, v157, 1.0
	v_fma_f32 v158, -v145, v158, 1.0
	v_fma_f32 v159, -v138, v159, 1.0
	v_fma_f32 v160, -v139, v160, 1.0
	v_fma_f32 v147, -v142, v147, 1.0
	v_fma_f32 v156, -v143, v156, 1.0
	v_log_f32_e32 v157, v157
	v_log_f32_e32 v158, v158
	v_log_f32_e32 v159, v159
	v_log_f32_e32 v160, v160
	v_fma_f32 v161, -v140, v161, 1.0
	v_fma_f32 v162, -v141, v162, 1.0
	v_log_f32_e32 v147, v147
	v_log_f32_e32 v156, v156
	v_log_f32_e32 v161, v161
	v_log_f32_e32 v162, v162
	s_mov_b32 s0, 0x28000
	v_cvt_pk_bf16_f32 v157, v157, v158
	v_cvt_pk_bf16_f32 v158, v159, v160
	v_add_co_u32_e32 v160, vcc, s0, v150
	v_cvt_pk_bf16_f32 v156, v147, v156
	v_cvt_pk_bf16_f32 v159, v161, v162
	v_addc_co_u32_e32 v161, vcc, 0, v151, vcc
	global_store_dwordx4 v[160:161], v[156:159], off
	v_mul_f32_e32 v147, v14, v152
	v_mul_f32_e32 v147, 0x3fb8aa3b, v147
	v_mul_f32_e32 v156, v15, v152
	v_mul_f32_e32 v156, 0x3fb8aa3b, v156
	v_exp_f32_e32 v147, v147
	v_exp_f32_e32 v156, v156
	v_mul_f32_e32 v157, v16, v152
	v_mul_f32_e32 v158, v17, v152
	v_add_f32_e32 v147, 1.0, v147
	v_add_f32_e32 v156, 1.0, v156
	v_rcp_f32_e32 v147, v147
	v_rcp_f32_e32 v156, v156
	v_mul_f32_e32 v159, v10, v152
	v_mul_f32_e32 v160, v11, v152
	v_fma_f32 v147, -v134, v147, 1.0
	v_fma_f32 v156, -v135, v156, 1.0
	v_log_f32_e32 v147, v147
	v_log_f32_e32 v156, v156
	v_mul_f32_e32 v161, v12, v152
	v_mul_f32_e32 v152, v13, v152
	v_mul_f32_e32 v157, 0x3fb8aa3b, v157
	v_cvt_pk_bf16_f32 v156, v147, v156
	v_mul_f32_e32 v147, v38, v153
	v_mul_f32_e32 v147, 0x3fb8aa3b, v147
	v_exp_f32_e32 v147, v147
	v_mul_f32_e32 v158, 0x3fb8aa3b, v158
	v_mul_f32_e32 v159, 0x3fb8aa3b, v159
	v_mul_f32_e32 v160, 0x3fb8aa3b, v160
	v_add_f32_e32 v147, 1.0, v147
	v_rcp_f32_e32 v147, v147
	v_mul_f32_e32 v161, 0x3fb8aa3b, v161
	v_mul_f32_e32 v152, 0x3fb8aa3b, v152
	v_exp_f32_e32 v157, v157
	v_fma_f32 v142, -v142, v147, 1.0
	v_mul_f32_e32 v147, v39, v153
	v_mul_f32_e32 v147, 0x3fb8aa3b, v147
	v_exp_f32_e32 v147, v147
	v_exp_f32_e32 v158, v158
	v_exp_f32_e32 v159, v159
	v_exp_f32_e32 v160, v160
	v_add_f32_e32 v147, 1.0, v147
	v_rcp_f32_e32 v147, v147
	v_exp_f32_e32 v161, v161
	v_exp_f32_e32 v152, v152
	v_add_f32_e32 v157, 1.0, v157
	v_fma_f32 v143, -v143, v147, 1.0
	v_mul_f32_e32 v147, v40, v153
	v_mul_f32_e32 v147, 0x3fb8aa3b, v147
	v_exp_f32_e32 v147, v147
	v_pk_add_f32 v[158:159], v[158:159], 1.0 op_sel_hi:[1,0]
	v_add_f32_e32 v160, 1.0, v160
	v_add_f32_e32 v147, 1.0, v147
	v_rcp_f32_e32 v147, v147
	v_add_f32_e32 v161, 1.0, v161
	v_add_f32_e32 v152, 1.0, v152
	v_rcp_f32_e32 v157, v157
	v_fma_f32 v144, -v144, v147, 1.0
	v_mul_f32_e32 v147, v41, v153
	v_mul_f32_e32 v147, 0x3fb8aa3b, v147
	v_exp_f32_e32 v147, v147
	v_rcp_f32_e32 v158, v158
	v_rcp_f32_e32 v159, v159
	v_rcp_f32_e32 v160, v160
	v_add_f32_e32 v147, 1.0, v147
	v_rcp_f32_e32 v147, v147
	v_rcp_f32_e32 v161, v161
	v_rcp_f32_e32 v152, v152
	v_fma_f32 v157, -v136, v157, 1.0
	v_fma_f32 v145, -v145, v147, 1.0
	v_mul_f32_e32 v147, v34, v153
	v_mul_f32_e32 v147, 0x3fb8aa3b, v147
	v_exp_f32_e32 v147, v147
	v_fma_f32 v158, -v137, v158, 1.0
	v_fma_f32 v159, -v130, v159, 1.0
	v_fma_f32 v160, -v131, v160, 1.0
	v_add_f32_e32 v147, 1.0, v147
	v_rcp_f32_e32 v147, v147
	v_fma_f32 v161, -v132, v161, 1.0
	v_fma_f32 v152, -v133, v152, 1.0
	v_log_f32_e32 v157, v157
	v_fma_f32 v138, -v138, v147, 1.0
	v_log_f32_e32 v147, v138
	v_mul_f32_e32 v138, v35, v153
	v_mul_f32_e32 v138, 0x3fb8aa3b, v138
	v_exp_f32_e32 v138, v138
	v_log_f32_e32 v158, v158
	v_log_f32_e32 v159, v159
	v_log_f32_e32 v160, v160
	v_add_f32_e32 v138, 1.0, v138
	v_rcp_f32_e32 v138, v138
	v_log_f32_e32 v161, v161
	v_log_f32_e32 v152, v152
	v_cvt_pk_bf16_f32 v157, v157, v158
	v_fma_f32 v138, -v139, v138, 1.0
	v_cvt_pk_bf16_f32 v158, v159, v160
	v_cvt_pk_bf16_f32 v159, v161, v152
	v_log_f32_e32 v152, v138
	v_mul_f32_e32 v138, v36, v153
	v_mul_f32_e32 v138, 0x3fb8aa3b, v138
	v_exp_f32_e32 v138, v138
	s_mov_b64 s[16:17], 0x28000
	v_lshl_add_u64 v[154:155], v[150:151], 0, s[16:17]
	global_store_dwordx4 v[154:155], v[156:159], off offset:256
	v_add_f32_e32 v138, 1.0, v138
	v_rcp_f32_e32 v138, v138
	v_log_f32_e32 v142, v142
	v_log_f32_e32 v143, v143
	v_log_f32_e32 v144, v144
	v_fma_f32 v138, -v140, v138, 1.0
	v_log_f32_e32 v156, v138
	v_mul_f32_e32 v138, v37, v153
	v_mul_f32_e32 v138, 0x3fb8aa3b, v138
	v_exp_f32_e32 v138, v138
	v_log_f32_e32 v145, v145
	s_mov_b32 s0, 0x2c000
	v_cvt_pk_bf16_f32 v140, v147, v152
	v_add_f32_e32 v138, 1.0, v138
	v_rcp_f32_e32 v138, v138
	v_cvt_pk_bf16_f32 v139, v144, v145
	s_mov_b64 s[16:17], 0x2c000
	v_lshl_add_u64 v[154:155], v[150:151], 0, s[16:17]
	v_fma_f32 v138, -v141, v138, 1.0
	v_log_f32_e32 v141, v138
	v_cvt_pk_bf16_f32 v138, v142, v143
	v_add_co_u32_e32 v142, vcc, s0, v150
	v_cvt_pk_bf16_f32 v141, v156, v141
	s_nop 0
	v_addc_co_u32_e32 v143, vcc, 0, v151, vcc
	global_store_dwordx4 v[142:143], v[138:141], off
	s_mov_b64 s[16:17], 0
	s_nop 0
	v_mul_f32_e32 v138, v6, v153
	v_mul_f32_e32 v138, 0x3fb8aa3b, v138
	v_exp_f32_e32 v138, v138
	s_nop 0
	v_add_f32_e32 v138, 1.0, v138
	v_rcp_f32_e32 v138, v138
	s_nop 0
	v_fma_f32 v134, -v134, v138, 1.0
	v_mul_f32_e32 v138, v7, v153
	v_mul_f32_e32 v138, 0x3fb8aa3b, v138
	v_exp_f32_e32 v138, v138
	v_log_f32_e32 v134, v134
	v_add_f32_e32 v138, 1.0, v138
	v_rcp_f32_e32 v138, v138
	s_nop 0
	v_fma_f32 v135, -v135, v138, 1.0
	v_mul_f32_e32 v138, v8, v153
	v_mul_f32_e32 v138, 0x3fb8aa3b, v138
	v_exp_f32_e32 v138, v138
	v_log_f32_e32 v135, v135
	v_add_f32_e32 v138, 1.0, v138
	v_rcp_f32_e32 v138, v138
	s_nop 0
	v_fma_f32 v136, -v136, v138, 1.0
	v_mul_f32_e32 v138, v9, v153
	v_mul_f32_e32 v138, 0x3fb8aa3b, v138
	v_exp_f32_e32 v138, v138
	v_log_f32_e32 v136, v136
	v_add_f32_e32 v138, 1.0, v138
	v_rcp_f32_e32 v138, v138
	s_nop 0
	v_fma_f32 v137, -v137, v138, 1.0
	v_mul_f32_e32 v138, v2, v153
	v_mul_f32_e32 v138, 0x3fb8aa3b, v138
	v_exp_f32_e32 v138, v138
	v_log_f32_e32 v137, v137
	v_add_f32_e32 v138, 1.0, v138
	v_rcp_f32_e32 v138, v138
	s_nop 0
	v_fma_f32 v130, -v130, v138, 1.0
	v_log_f32_e32 v138, v130
	v_mul_f32_e32 v130, v3, v153
	v_mul_f32_e32 v130, 0x3fb8aa3b, v130
	v_exp_f32_e32 v130, v130
	s_nop 0
	v_add_f32_e32 v130, 1.0, v130
	v_rcp_f32_e32 v130, v130
	s_nop 0
	v_fma_f32 v130, -v131, v130, 1.0
	v_log_f32_e32 v139, v130
	v_mul_f32_e32 v130, v4, v153
	v_mul_f32_e32 v130, 0x3fb8aa3b, v130
	v_exp_f32_e32 v130, v130
	v_cvt_pk_bf16_f32 v131, v136, v137
	v_add_f32_e32 v130, 1.0, v130
	v_rcp_f32_e32 v130, v130
	s_nop 0
	v_fma_f32 v130, -v132, v130, 1.0
	v_log_f32_e32 v140, v130
	v_mul_f32_e32 v130, v5, v153
	v_mul_f32_e32 v130, 0x3fb8aa3b, v130
	v_exp_f32_e32 v130, v130
	v_cvt_pk_bf16_f32 v132, v138, v139
	v_add_f32_e32 v130, 1.0, v130
	v_rcp_f32_e32 v130, v130
	s_nop 0
	v_fma_f32 v130, -v133, v130, 1.0
	v_log_f32_e32 v133, v130
	v_cvt_pk_bf16_f32 v130, v134, v135
	v_cvt_pk_bf16_f32 v133, v140, v133
	global_store_dwordx4 v[154:155], v[130:133], off offset:256
.LBB0_848:
	s_andn2_b64 vcc, exec, s[16:17]
	s_cbranch_vccnz .LBB0_850
	v_lshl_add_u32 v138, s13, 10, v233
	ds_read2_b32 v[134:135], v138 offset1:16
	v_ashrrev_i32_e32 v147, 31, v146
	v_lshl_add_u64 v[132:133], v[148:149], 1, s[6:7]
	v_lshlrev_b64 v[130:131], 10, v[146:147]
	v_lshl_add_u64 v[130:131], v[132:133], 0, v[130:131]
	s_waitcnt lgkmcnt(0)
	v_pk_mul_f32 v[136:137], v[126:127], v[134:135] op_sel_hi:[1,0]
	s_mov_b32 s0, 0x20000
	v_mul_f32_e32 v139, 0xbfb8aa3b, v136
	v_exp_f32_e32 v139, v139
	s_mov_b64 s[16:17], 0x20000
	v_add_f32_e32 v139, 1.0, v139
	v_rcp_f32_e32 v140, v139
	v_mul_f32_e32 v139, 0xbfb8aa3b, v137
	v_exp_f32_e32 v139, v139
	s_nop 0
	v_add_f32_e32 v139, 1.0, v139
	v_rcp_f32_e32 v141, v139
	s_nop 0
	v_pk_mul_f32 v[136:137], v[136:137], v[140:141]
	v_pk_mul_f32 v[140:141], v[128:129], v[134:135] op_sel_hi:[1,0]
	s_nop 0
	v_mul_f32_e32 v139, 0xbfb8aa3b, v140
	v_exp_f32_e32 v139, v139
	s_nop 0
	v_add_f32_e32 v139, 1.0, v139
	v_rcp_f32_e32 v142, v139
	v_mul_f32_e32 v139, 0xbfb8aa3b, v141
	v_exp_f32_e32 v139, v139
	s_nop 0
	v_add_f32_e32 v139, 1.0, v139
	v_rcp_f32_e32 v143, v139
	s_nop 0
	v_pk_mul_f32 v[142:143], v[140:141], v[142:143]
	v_pk_mul_f32 v[140:141], v[122:123], v[134:135] op_sel_hi:[1,0]
	s_nop 0
	v_mul_f32_e32 v139, 0xbfb8aa3b, v140
	v_exp_f32_e32 v139, v139
	s_nop 0
	v_add_f32_e32 v139, 1.0, v139
	v_rcp_f32_e32 v144, v139
	v_mul_f32_e32 v139, 0xbfb8aa3b, v141
	v_exp_f32_e32 v139, v139
	s_nop 0
	v_add_f32_e32 v139, 1.0, v139
	v_rcp_f32_e32 v145, v139
	s_nop 0
	v_pk_mul_f32 v[144:145], v[140:141], v[144:145]
	v_pk_mul_f32 v[140:141], v[124:125], v[134:135] op_sel_hi:[1,0]
	s_nop 0
	v_mul_f32_e32 v139, 0xbfb8aa3b, v140
	v_exp_f32_e32 v139, v139
	s_nop 0
	v_add_f32_e32 v139, 1.0, v139
	v_rcp_f32_e32 v150, v139
	v_mul_f32_e32 v139, 0xbfb8aa3b, v141
	v_exp_f32_e32 v139, v139
	s_nop 0
	v_add_f32_e32 v139, 1.0, v139
	v_rcp_f32_e32 v151, v139
	s_nop 0
	v_pk_mul_f32 v[150:151], v[140:141], v[150:151]
	v_cvt_pk_bf16_f32 v140, v136, v137
	v_pk_mul_f32 v[136:137], v[94:95], v[134:135] op_sel_hi:[1,0]
	v_cvt_pk_bf16_f32 v141, v142, v143
	v_mul_f32_e32 v139, 0xbfb8aa3b, v136
	v_exp_f32_e32 v139, v139
	v_cvt_pk_bf16_f32 v142, v144, v145
	v_cvt_pk_bf16_f32 v143, v150, v151
	global_store_dwordx4 v[130:131], v[140:143], off
	v_add_f32_e32 v139, 1.0, v139
	s_nop 0
	v_rcp_f32_e32 v140, v139
	v_mul_f32_e32 v139, 0xbfb8aa3b, v137
	v_exp_f32_e32 v139, v139
	s_nop 0
	v_add_f32_e32 v139, 1.0, v139
	v_rcp_f32_e32 v141, v139
	s_nop 0
	v_pk_mul_f32 v[136:137], v[136:137], v[140:141]
	v_pk_mul_f32 v[140:141], v[96:97], v[134:135] op_sel_hi:[1,0]
	s_nop 0
	v_mul_f32_e32 v139, 0xbfb8aa3b, v140
	v_exp_f32_e32 v139, v139
	s_nop 0
	v_add_f32_e32 v139, 1.0, v139
	v_rcp_f32_e32 v142, v139
	v_mul_f32_e32 v139, 0xbfb8aa3b, v141
	v_exp_f32_e32 v139, v139
	s_nop 0
	v_add_f32_e32 v139, 1.0, v139
	v_rcp_f32_e32 v143, v139
	s_nop 0
	v_pk_mul_f32 v[142:143], v[140:141], v[142:143]
	v_pk_mul_f32 v[140:141], v[90:91], v[134:135] op_sel_hi:[1,0]
	s_nop 0
	v_mul_f32_e32 v139, 0xbfb8aa3b, v140
	v_exp_f32_e32 v139, v139
	s_nop 0
	v_add_f32_e32 v139, 1.0, v139
	v_rcp_f32_e32 v144, v139
	v_mul_f32_e32 v139, 0xbfb8aa3b, v141
	v_exp_f32_e32 v139, v139
	s_nop 0
	v_add_f32_e32 v139, 1.0, v139
	v_rcp_f32_e32 v145, v139
	s_nop 0
	v_pk_mul_f32 v[144:145], v[140:141], v[144:145]
	v_pk_mul_f32 v[140:141], v[92:93], v[134:135] op_sel_hi:[1,0]
	s_nop 0
	v_mul_f32_e32 v134, 0xbfb8aa3b, v140
	v_exp_f32_e32 v134, v134
	s_nop 0
	v_add_f32_e32 v134, 1.0, v134
	v_rcp_f32_e32 v150, v134
	v_mul_f32_e32 v134, 0xbfb8aa3b, v141
	v_exp_f32_e32 v134, v134
	s_nop 0
	v_add_f32_e32 v134, 1.0, v134
	v_rcp_f32_e32 v151, v134
	v_mov_b32_e32 v134, v135
	v_pk_mul_f32 v[150:151], v[140:141], v[150:151]
	v_cvt_pk_bf16_f32 v140, v136, v137
	v_cvt_pk_bf16_f32 v141, v142, v143
	v_cvt_pk_bf16_f32 v142, v144, v145
	v_cvt_pk_bf16_f32 v143, v150, v151
	global_store_dwordx4 v[130:131], v[140:143], off offset:256
	v_or_b32_e32 v136, 16, v146
	v_ashrrev_i32_e32 v137, 31, v136
	v_pk_mul_f32 v[140:141], v[118:119], v[134:135] op_sel_hi:[1,0]
	v_lshlrev_b64 v[136:137], 10, v[136:137]
	v_mul_f32_e32 v135, 0xbfb8aa3b, v140
	v_exp_f32_e32 v135, v135
	v_lshl_add_u64 v[136:137], v[132:133], 0, v[136:137]
	v_add_f32_e32 v135, 1.0, v135
	v_rcp_f32_e32 v142, v135
	v_mul_f32_e32 v135, 0xbfb8aa3b, v141
	v_exp_f32_e32 v135, v135
	s_nop 0
	v_add_f32_e32 v135, 1.0, v135
	v_rcp_f32_e32 v143, v135
	s_nop 0
	v_pk_mul_f32 v[140:141], v[140:141], v[142:143]
	v_pk_mul_f32 v[142:143], v[120:121], v[134:135] op_sel_hi:[1,0]
	v_cvt_pk_bf16_f32 v140, v140, v141
	v_mul_f32_e32 v135, 0xbfb8aa3b, v142
	v_exp_f32_e32 v135, v135
	s_nop 0
	v_add_f32_e32 v135, 1.0, v135
	v_rcp_f32_e32 v144, v135
	v_mul_f32_e32 v135, 0xbfb8aa3b, v143
	v_exp_f32_e32 v135, v135
	s_nop 0
	v_add_f32_e32 v135, 1.0, v135
	v_rcp_f32_e32 v145, v135
	s_nop 0
	v_pk_mul_f32 v[142:143], v[142:143], v[144:145]
	v_pk_mul_f32 v[144:145], v[114:115], v[134:135] op_sel_hi:[1,0]
	v_cvt_pk_bf16_f32 v141, v142, v143
	v_mul_f32_e32 v135, 0xbfb8aa3b, v144
	v_exp_f32_e32 v135, v135
	s_nop 0
	v_add_f32_e32 v135, 1.0, v135
	v_rcp_f32_e32 v150, v135
	v_mul_f32_e32 v135, 0xbfb8aa3b, v145
	v_exp_f32_e32 v135, v135
	s_nop 0
	v_add_f32_e32 v135, 1.0, v135
	v_rcp_f32_e32 v151, v135
	s_nop 0
	v_pk_mul_f32 v[144:145], v[144:145], v[150:151]
	v_pk_mul_f32 v[150:151], v[116:117], v[134:135] op_sel_hi:[1,0]
	v_cvt_pk_bf16_f32 v142, v144, v145
	v_mul_f32_e32 v135, 0xbfb8aa3b, v150
	v_exp_f32_e32 v135, v135
	s_nop 0
	v_add_f32_e32 v135, 1.0, v135
	v_rcp_f32_e32 v152, v135
	v_mul_f32_e32 v135, 0xbfb8aa3b, v151
	v_exp_f32_e32 v135, v135
	s_nop 0
	v_add_f32_e32 v135, 1.0, v135
	v_rcp_f32_e32 v153, v135
	s_nop 0
	v_pk_mul_f32 v[150:151], v[150:151], v[152:153]
	s_nop 0
	v_cvt_pk_bf16_f32 v143, v150, v151
	global_store_dwordx4 v[136:137], v[140:143], off
	s_nop 1
	v_pk_mul_f32 v[140:141], v[86:87], v[134:135] op_sel_hi:[1,0]
	s_nop 0
	v_mul_f32_e32 v135, 0xbfb8aa3b, v140
	v_exp_f32_e32 v135, v135
	s_nop 0
	v_add_f32_e32 v135, 1.0, v135
	v_rcp_f32_e32 v142, v135
	v_mul_f32_e32 v135, 0xbfb8aa3b, v141
	v_exp_f32_e32 v135, v135
	s_nop 0
	v_add_f32_e32 v135, 1.0, v135
	v_rcp_f32_e32 v143, v135
	s_nop 0
	v_pk_mul_f32 v[140:141], v[140:141], v[142:143]
	v_pk_mul_f32 v[142:143], v[88:89], v[134:135] op_sel_hi:[1,0]
	v_cvt_pk_bf16_f32 v140, v140, v141
	v_mul_f32_e32 v135, 0xbfb8aa3b, v142
	v_exp_f32_e32 v135, v135
	s_nop 0
	v_add_f32_e32 v135, 1.0, v135
	v_rcp_f32_e32 v144, v135
	v_mul_f32_e32 v135, 0xbfb8aa3b, v143
	v_exp_f32_e32 v135, v135
	s_nop 0
	v_add_f32_e32 v135, 1.0, v135
	v_rcp_f32_e32 v145, v135
	s_nop 0
	v_pk_mul_f32 v[142:143], v[142:143], v[144:145]
	v_pk_mul_f32 v[144:145], v[82:83], v[134:135] op_sel_hi:[1,0]
	v_cvt_pk_bf16_f32 v141, v142, v143
	v_mul_f32_e32 v135, 0xbfb8aa3b, v144
	v_exp_f32_e32 v135, v135
	s_nop 0
	v_add_f32_e32 v135, 1.0, v135
	v_rcp_f32_e32 v150, v135
	v_mul_f32_e32 v135, 0xbfb8aa3b, v145
	v_exp_f32_e32 v135, v135
	s_nop 0
	v_add_f32_e32 v135, 1.0, v135
	v_rcp_f32_e32 v151, v135
	v_pk_mul_f32 v[134:135], v[84:85], v[134:135] op_sel_hi:[1,0]
	v_pk_mul_f32 v[144:145], v[144:145], v[150:151]
	v_mul_f32_e32 v139, 0xbfb8aa3b, v134
	v_exp_f32_e32 v139, v139
	v_cvt_pk_bf16_f32 v142, v144, v145
	v_add_f32_e32 v139, 1.0, v139
	v_rcp_f32_e32 v150, v139
	v_mul_f32_e32 v139, 0xbfb8aa3b, v135
	v_exp_f32_e32 v139, v139
	s_nop 0
	v_add_f32_e32 v139, 1.0, v139
	v_rcp_f32_e32 v151, v139
	s_nop 0
	v_pk_mul_f32 v[134:135], v[134:135], v[150:151]
	s_nop 0
	v_cvt_pk_bf16_f32 v143, v134, v135
	ds_read2_b32 v[134:135], v138 offset0:32 offset1:48
	global_store_dwordx4 v[136:137], v[140:143], off offset:256
	v_or_b32_e32 v136, 32, v146
	v_ashrrev_i32_e32 v137, 31, v136
	v_lshlrev_b64 v[136:137], 10, v[136:137]
	s_waitcnt lgkmcnt(0)
	v_pk_mul_f32 v[140:141], v[110:111], v[134:135] op_sel_hi:[1,0]
	v_lshl_add_u64 v[136:137], v[132:133], 0, v[136:137]
	v_mul_f32_e32 v139, 0xbfb8aa3b, v140
	v_exp_f32_e32 v139, v139
	s_nop 0
	v_add_f32_e32 v139, 1.0, v139
	v_rcp_f32_e32 v142, v139
	v_mul_f32_e32 v139, 0xbfb8aa3b, v141
	v_exp_f32_e32 v139, v139
	s_nop 0
	v_add_f32_e32 v139, 1.0, v139
	v_rcp_f32_e32 v143, v139
	s_nop 0
	v_pk_mul_f32 v[140:141], v[140:141], v[142:143]
	v_pk_mul_f32 v[142:143], v[112:113], v[134:135] op_sel_hi:[1,0]
	v_cvt_pk_bf16_f32 v140, v140, v141
	v_mul_f32_e32 v139, 0xbfb8aa3b, v142
	v_exp_f32_e32 v139, v139
	s_nop 0
	v_add_f32_e32 v139, 1.0, v139
	v_rcp_f32_e32 v144, v139
	v_mul_f32_e32 v139, 0xbfb8aa3b, v143
	v_exp_f32_e32 v139, v139
	s_nop 0
	v_add_f32_e32 v139, 1.0, v139
	v_rcp_f32_e32 v145, v139
	s_nop 0
	v_pk_mul_f32 v[142:143], v[142:143], v[144:145]
	v_pk_mul_f32 v[144:145], v[106:107], v[134:135] op_sel_hi:[1,0]
	v_cvt_pk_bf16_f32 v141, v142, v143
	v_mul_f32_e32 v139, 0xbfb8aa3b, v144
	v_exp_f32_e32 v139, v139
	s_nop 0
	v_add_f32_e32 v139, 1.0, v139
	v_rcp_f32_e32 v150, v139
	v_mul_f32_e32 v139, 0xbfb8aa3b, v145
	v_exp_f32_e32 v139, v139
	s_nop 0
	v_add_f32_e32 v139, 1.0, v139
	v_rcp_f32_e32 v151, v139
	s_nop 0
	v_pk_mul_f32 v[144:145], v[144:145], v[150:151]
	v_pk_mul_f32 v[150:151], v[108:109], v[134:135] op_sel_hi:[1,0]
	v_cvt_pk_bf16_f32 v142, v144, v145
	v_mul_f32_e32 v139, 0xbfb8aa3b, v150
	v_exp_f32_e32 v139, v139
	s_nop 0
	v_add_f32_e32 v139, 1.0, v139
	v_rcp_f32_e32 v152, v139
	v_mul_f32_e32 v139, 0xbfb8aa3b, v151
	v_exp_f32_e32 v139, v139
	s_nop 0
	v_add_f32_e32 v139, 1.0, v139
	v_rcp_f32_e32 v153, v139
	s_nop 0
	v_pk_mul_f32 v[150:151], v[150:151], v[152:153]
	s_nop 0
	v_cvt_pk_bf16_f32 v143, v150, v151
	global_store_dwordx4 v[136:137], v[140:143], off
	s_nop 1
	v_pk_mul_f32 v[140:141], v[78:79], v[134:135] op_sel_hi:[1,0]
	s_nop 0
	v_mul_f32_e32 v139, 0xbfb8aa3b, v140
	v_exp_f32_e32 v139, v139
	s_nop 0
	v_add_f32_e32 v139, 1.0, v139
	v_rcp_f32_e32 v142, v139
	v_mul_f32_e32 v139, 0xbfb8aa3b, v141
	v_exp_f32_e32 v139, v139
	s_nop 0
	v_add_f32_e32 v139, 1.0, v139
	v_rcp_f32_e32 v143, v139
	s_nop 0
	v_pk_mul_f32 v[140:141], v[140:141], v[142:143]
	v_pk_mul_f32 v[142:143], v[80:81], v[134:135] op_sel_hi:[1,0]
	v_cvt_pk_bf16_f32 v140, v140, v141
	v_mul_f32_e32 v139, 0xbfb8aa3b, v142
	v_exp_f32_e32 v139, v139
	s_nop 0
	v_add_f32_e32 v139, 1.0, v139
	v_rcp_f32_e32 v144, v139
	v_mul_f32_e32 v139, 0xbfb8aa3b, v143
	v_exp_f32_e32 v139, v139
	s_nop 0
	v_add_f32_e32 v139, 1.0, v139
	v_rcp_f32_e32 v145, v139
	s_nop 0
	v_pk_mul_f32 v[142:143], v[142:143], v[144:145]
	v_pk_mul_f32 v[144:145], v[74:75], v[134:135] op_sel_hi:[1,0]
	v_cvt_pk_bf16_f32 v141, v142, v143
	v_mul_f32_e32 v139, 0xbfb8aa3b, v144
	v_exp_f32_e32 v139, v139
	s_nop 0
	v_add_f32_e32 v139, 1.0, v139
	v_rcp_f32_e32 v150, v139
	v_mul_f32_e32 v139, 0xbfb8aa3b, v145
	v_exp_f32_e32 v139, v139
	s_nop 0
	v_add_f32_e32 v139, 1.0, v139
	v_rcp_f32_e32 v151, v139
	s_nop 0
	v_pk_mul_f32 v[144:145], v[144:145], v[150:151]
	v_pk_mul_f32 v[150:151], v[76:77], v[134:135] op_sel_hi:[1,0]
	v_cvt_pk_bf16_f32 v142, v144, v145
	v_mul_f32_e32 v134, 0xbfb8aa3b, v150
	v_exp_f32_e32 v134, v134
	s_nop 0
	v_add_f32_e32 v134, 1.0, v134
	v_rcp_f32_e32 v152, v134
	v_mul_f32_e32 v134, 0xbfb8aa3b, v151
	v_exp_f32_e32 v134, v134
	s_nop 0
	v_add_f32_e32 v134, 1.0, v134
	v_rcp_f32_e32 v153, v134
	v_mov_b32_e32 v134, v135
	v_pk_mul_f32 v[150:151], v[150:151], v[152:153]
	s_nop 0
	v_cvt_pk_bf16_f32 v143, v150, v151
	global_store_dwordx4 v[136:137], v[140:143], off offset:256
	v_or_b32_e32 v136, 48, v146
	v_ashrrev_i32_e32 v137, 31, v136
	v_lshlrev_b64 v[136:137], 10, v[136:137]
	v_lshl_add_u64 v[132:133], v[132:133], 0, v[136:137]
	v_pk_mul_f32 v[136:137], v[102:103], v[134:135] op_sel_hi:[1,0]
	s_nop 0
	v_mul_f32_e32 v135, 0xbfb8aa3b, v136
	v_exp_f32_e32 v135, v135
	s_nop 0
	v_add_f32_e32 v135, 1.0, v135
	v_rcp_f32_e32 v140, v135
	v_mul_f32_e32 v135, 0xbfb8aa3b, v137
	v_exp_f32_e32 v135, v135
	s_nop 0
	v_add_f32_e32 v135, 1.0, v135
	v_rcp_f32_e32 v141, v135
	s_nop 0
	v_pk_mul_f32 v[136:137], v[136:137], v[140:141]
	v_pk_mul_f32 v[140:141], v[104:105], v[134:135] op_sel_hi:[1,0]
	s_nop 0
	v_mul_f32_e32 v135, 0xbfb8aa3b, v140
	v_exp_f32_e32 v135, v135
	s_nop 0
	v_add_f32_e32 v135, 1.0, v135
	v_rcp_f32_e32 v142, v135
	v_mul_f32_e32 v135, 0xbfb8aa3b, v141
	v_exp_f32_e32 v135, v135
	s_nop 0
	v_add_f32_e32 v135, 1.0, v135
	v_rcp_f32_e32 v143, v135
	s_nop 0
	v_pk_mul_f32 v[142:143], v[140:141], v[142:143]
	v_pk_mul_f32 v[140:141], v[98:99], v[134:135] op_sel_hi:[1,0]
	s_nop 0
	v_mul_f32_e32 v135, 0xbfb8aa3b, v140
	v_exp_f32_e32 v135, v135
	s_nop 0
	v_add_f32_e32 v135, 1.0, v135
	v_rcp_f32_e32 v144, v135
	v_mul_f32_e32 v135, 0xbfb8aa3b, v141
	v_exp_f32_e32 v135, v135
	s_nop 0
	v_add_f32_e32 v135, 1.0, v135
	v_rcp_f32_e32 v145, v135
	s_nop 0
	v_pk_mul_f32 v[144:145], v[140:141], v[144:145]
	v_pk_mul_f32 v[140:141], v[100:101], v[134:135] op_sel_hi:[1,0]
	s_nop 0
	v_mul_f32_e32 v135, 0xbfb8aa3b, v140
	v_exp_f32_e32 v135, v135
	s_nop 0
	v_add_f32_e32 v135, 1.0, v135
	v_rcp_f32_e32 v150, v135
	v_mul_f32_e32 v135, 0xbfb8aa3b, v141
	v_exp_f32_e32 v135, v135
	s_nop 0
	v_add_f32_e32 v135, 1.0, v135
	v_rcp_f32_e32 v151, v135
	s_nop 0
	v_pk_mul_f32 v[150:151], v[140:141], v[150:151]
	v_cvt_pk_bf16_f32 v140, v136, v137
	v_pk_mul_f32 v[136:137], v[70:71], v[134:135] op_sel_hi:[1,0]
	v_cvt_pk_bf16_f32 v141, v142, v143
	v_mul_f32_e32 v135, 0xbfb8aa3b, v136
	v_exp_f32_e32 v135, v135
	v_cvt_pk_bf16_f32 v142, v144, v145
	v_cvt_pk_bf16_f32 v143, v150, v151
	global_store_dwordx4 v[132:133], v[140:143], off
	v_add_f32_e32 v135, 1.0, v135
	s_nop 0
	v_rcp_f32_e32 v140, v135
	v_mul_f32_e32 v135, 0xbfb8aa3b, v137
	v_exp_f32_e32 v135, v135
	s_nop 0
	v_add_f32_e32 v135, 1.0, v135
	v_rcp_f32_e32 v141, v135
	s_nop 0
	v_pk_mul_f32 v[136:137], v[136:137], v[140:141]
	v_pk_mul_f32 v[140:141], v[72:73], v[134:135] op_sel_hi:[1,0]
	s_nop 0
	v_mul_f32_e32 v135, 0xbfb8aa3b, v140
	v_exp_f32_e32 v135, v135
	s_nop 0
	v_add_f32_e32 v135, 1.0, v135
	v_rcp_f32_e32 v142, v135
	v_mul_f32_e32 v135, 0xbfb8aa3b, v141
	v_exp_f32_e32 v135, v135
	s_nop 0
	v_add_f32_e32 v135, 1.0, v135
	v_rcp_f32_e32 v143, v135
	s_nop 0
	v_pk_mul_f32 v[140:141], v[140:141], v[142:143]
	v_pk_mul_f32 v[142:143], v[58:59], v[134:135] op_sel_hi:[1,0]
	s_nop 0
	v_mul_f32_e32 v135, 0xbfb8aa3b, v142
	v_exp_f32_e32 v135, v135
	s_nop 0
	v_add_f32_e32 v135, 1.0, v135
	v_rcp_f32_e32 v144, v135
	v_mul_f32_e32 v135, 0xbfb8aa3b, v143
	v_exp_f32_e32 v135, v135
	s_nop 0
	v_add_f32_e32 v135, 1.0, v135
	v_rcp_f32_e32 v145, v135
	v_pk_mul_f32 v[134:135], v[60:61], v[134:135] op_sel_hi:[1,0]
	v_pk_mul_f32 v[142:143], v[142:143], v[144:145]
	v_mul_f32_e32 v139, 0xbfb8aa3b, v134
	v_exp_f32_e32 v139, v139
	s_nop 0
	v_add_f32_e32 v139, 1.0, v139
	v_rcp_f32_e32 v144, v139
	v_mul_f32_e32 v139, 0xbfb8aa3b, v135
	v_exp_f32_e32 v139, v139
	s_nop 0
	v_add_f32_e32 v139, 1.0, v139
	v_rcp_f32_e32 v145, v139
	s_nop 0
	v_pk_mul_f32 v[144:145], v[134:135], v[144:145]
	v_cvt_pk_bf16_f32 v134, v136, v137
	v_cvt_pk_bf16_f32 v135, v140, v141
	v_cvt_pk_bf16_f32 v136, v142, v143
	v_cvt_pk_bf16_f32 v137, v144, v145
	global_store_dwordx4 v[132:133], v[134:137], off offset:256
	ds_read2_b32 v[132:133], v138 offset0:128 offset1:144
	s_nop 0
	v_lshl_add_u64 v[134:135], v[130:131], 0, s[16:17]
	s_mov_b64 s[16:17], 0x24000
	s_waitcnt lgkmcnt(0)
	v_pk_mul_f32 v[136:137], v[66:67], v[132:133] op_sel_hi:[1,0]
	s_nop 0
	v_mul_f32_e32 v139, 0xbfb8aa3b, v136
	v_exp_f32_e32 v139, v139
	s_nop 0
	v_add_f32_e32 v139, 1.0, v139
	v_rcp_f32_e32 v140, v139
	v_mul_f32_e32 v139, 0xbfb8aa3b, v137
	v_exp_f32_e32 v139, v139
	s_nop 0
	v_add_f32_e32 v139, 1.0, v139
	v_rcp_f32_e32 v141, v139
	s_nop 0
	v_pk_mul_f32 v[136:137], v[136:137], v[140:141]
	v_pk_mul_f32 v[140:141], v[68:69], v[132:133] op_sel_hi:[1,0]
	s_nop 0
	v_mul_f32_e32 v139, 0xbfb8aa3b, v140
	v_exp_f32_e32 v139, v139
	s_nop 0
	v_add_f32_e32 v139, 1.0, v139
	v_rcp_f32_e32 v142, v139
	v_mul_f32_e32 v139, 0xbfb8aa3b, v141
	v_exp_f32_e32 v139, v139
	s_nop 0
	v_add_f32_e32 v139, 1.0, v139
	v_rcp_f32_e32 v143, v139
	s_nop 0
	v_pk_mul_f32 v[142:143], v[140:141], v[142:143]
	v_pk_mul_f32 v[140:141], v[62:63], v[132:133] op_sel_hi:[1,0]
	s_nop 0
	v_mul_f32_e32 v139, 0xbfb8aa3b, v140
	v_exp_f32_e32 v139, v139
	s_nop 0
	v_add_f32_e32 v139, 1.0, v139
	v_rcp_f32_e32 v144, v139
	v_mul_f32_e32 v139, 0xbfb8aa3b, v141
	v_exp_f32_e32 v139, v139
	s_nop 0
	v_add_f32_e32 v139, 1.0, v139
	v_rcp_f32_e32 v145, v139
	s_nop 0
	v_pk_mul_f32 v[144:145], v[140:141], v[144:145]
	v_pk_mul_f32 v[140:141], v[64:65], v[132:133] op_sel_hi:[1,0]
	s_nop 0
	v_mul_f32_e32 v139, 0xbfb8aa3b, v140
	v_exp_f32_e32 v139, v139
	s_nop 0
	v_add_f32_e32 v139, 1.0, v139
	v_rcp_f32_e32 v150, v139
	v_mul_f32_e32 v139, 0xbfb8aa3b, v141
	v_exp_f32_e32 v139, v139
	s_nop 0
	v_add_f32_e32 v139, 1.0, v139
	v_rcp_f32_e32 v151, v139
	s_nop 0
	v_pk_mul_f32 v[150:151], v[140:141], v[150:151]
	v_cvt_pk_bf16_f32 v140, v136, v137
	v_add_co_u32_e32 v136, vcc, s0, v130
	v_cvt_pk_bf16_f32 v141, v142, v143
	v_cvt_pk_bf16_f32 v142, v144, v145
	v_cvt_pk_bf16_f32 v143, v150, v151
	v_addc_co_u32_e32 v137, vcc, 0, v131, vcc
	global_store_dwordx4 v[136:137], v[140:143], off
	v_pk_mul_f32 v[136:137], v[30:31], v[132:133] op_sel_hi:[1,0]
	s_mov_b32 s0, 0x24000
	v_mul_f32_e32 v139, 0xbfb8aa3b, v136
	v_exp_f32_e32 v139, v139
	s_nop 0
	v_add_f32_e32 v139, 1.0, v139
	v_rcp_f32_e32 v140, v139
	v_mul_f32_e32 v139, 0xbfb8aa3b, v137
	v_exp_f32_e32 v139, v139
	s_nop 0
	v_add_f32_e32 v139, 1.0, v139
	v_rcp_f32_e32 v141, v139
	s_nop 0
	v_pk_mul_f32 v[136:137], v[136:137], v[140:141]
	v_pk_mul_f32 v[140:141], v[32:33], v[132:133] op_sel_hi:[1,0]
	s_nop 0
	v_mul_f32_e32 v139, 0xbfb8aa3b, v140
	v_exp_f32_e32 v139, v139
	s_nop 0
	v_add_f32_e32 v139, 1.0, v139
	v_rcp_f32_e32 v142, v139
	v_mul_f32_e32 v139, 0xbfb8aa3b, v141
	v_exp_f32_e32 v139, v139
	s_nop 0
	v_add_f32_e32 v139, 1.0, v139
	v_rcp_f32_e32 v143, v139
	s_nop 0
	v_pk_mul_f32 v[142:143], v[140:141], v[142:143]
	v_pk_mul_f32 v[140:141], v[26:27], v[132:133] op_sel_hi:[1,0]
	s_nop 0
	v_mul_f32_e32 v139, 0xbfb8aa3b, v140
	v_exp_f32_e32 v139, v139
	s_nop 0
	v_add_f32_e32 v139, 1.0, v139
	v_rcp_f32_e32 v144, v139
	v_mul_f32_e32 v139, 0xbfb8aa3b, v141
	v_exp_f32_e32 v139, v139
	s_nop 0
	v_add_f32_e32 v139, 1.0, v139
	v_rcp_f32_e32 v145, v139
	s_nop 0
	v_pk_mul_f32 v[144:145], v[140:141], v[144:145]
	v_pk_mul_f32 v[140:141], v[28:29], v[132:133] op_sel_hi:[1,0]
	s_nop 0
	v_mul_f32_e32 v132, 0xbfb8aa3b, v140
	v_exp_f32_e32 v132, v132
	s_nop 0
	v_add_f32_e32 v132, 1.0, v132
	v_rcp_f32_e32 v150, v132
	v_mul_f32_e32 v132, 0xbfb8aa3b, v141
	v_exp_f32_e32 v132, v132
	s_nop 0
	v_add_f32_e32 v132, 1.0, v132
	v_rcp_f32_e32 v151, v132
	v_mov_b32_e32 v132, v133
	v_pk_mul_f32 v[150:151], v[140:141], v[150:151]
	v_cvt_pk_bf16_f32 v140, v136, v137
	v_pk_mul_f32 v[136:137], v[54:55], v[132:133] op_sel_hi:[1,0]
	v_cvt_pk_bf16_f32 v141, v142, v143
	v_mul_f32_e32 v133, 0xbfb8aa3b, v136
	v_exp_f32_e32 v133, v133
	v_cvt_pk_bf16_f32 v142, v144, v145
	v_cvt_pk_bf16_f32 v143, v150, v151
	global_store_dwordx4 v[134:135], v[140:143], off offset:256
	v_add_f32_e32 v133, 1.0, v133
	v_lshl_add_u64 v[134:135], v[130:131], 0, s[16:17]
	v_rcp_f32_e32 v140, v133
	v_mul_f32_e32 v133, 0xbfb8aa3b, v137
	v_exp_f32_e32 v133, v133
	s_mov_b64 s[16:17], 0x28000
	v_add_f32_e32 v133, 1.0, v133
	v_rcp_f32_e32 v141, v133
	s_nop 0
	v_pk_mul_f32 v[136:137], v[136:137], v[140:141]
	v_pk_mul_f32 v[140:141], v[56:57], v[132:133] op_sel_hi:[1,0]
	s_nop 0
	v_mul_f32_e32 v133, 0xbfb8aa3b, v140
	v_exp_f32_e32 v133, v133
	s_nop 0
	v_add_f32_e32 v133, 1.0, v133
	v_rcp_f32_e32 v142, v133
	v_mul_f32_e32 v133, 0xbfb8aa3b, v141
	v_exp_f32_e32 v133, v133
	s_nop 0
	v_add_f32_e32 v133, 1.0, v133
	v_rcp_f32_e32 v143, v133
	s_nop 0
	v_pk_mul_f32 v[142:143], v[140:141], v[142:143]
	v_pk_mul_f32 v[140:141], v[50:51], v[132:133] op_sel_hi:[1,0]
	s_nop 0
	v_mul_f32_e32 v133, 0xbfb8aa3b, v140
	v_exp_f32_e32 v133, v133
	s_nop 0
	v_add_f32_e32 v133, 1.0, v133
	v_rcp_f32_e32 v144, v133
	v_mul_f32_e32 v133, 0xbfb8aa3b, v141
	v_exp_f32_e32 v133, v133
	s_nop 0
	v_add_f32_e32 v133, 1.0, v133
	v_rcp_f32_e32 v145, v133
	s_nop 0
	v_pk_mul_f32 v[144:145], v[140:141], v[144:145]
	v_pk_mul_f32 v[140:141], v[52:53], v[132:133] op_sel_hi:[1,0]
	s_nop 0
	v_mul_f32_e32 v133, 0xbfb8aa3b, v140
	v_exp_f32_e32 v133, v133
	s_nop 0
	v_add_f32_e32 v133, 1.0, v133
	v_rcp_f32_e32 v150, v133
	v_mul_f32_e32 v133, 0xbfb8aa3b, v141
	v_exp_f32_e32 v133, v133
	s_nop 0
	v_add_f32_e32 v133, 1.0, v133
	v_rcp_f32_e32 v151, v133
	s_nop 0
	v_pk_mul_f32 v[150:151], v[140:141], v[150:151]
	v_cvt_pk_bf16_f32 v140, v136, v137
	v_add_co_u32_e32 v136, vcc, s0, v130
	v_cvt_pk_bf16_f32 v141, v142, v143
	v_cvt_pk_bf16_f32 v142, v144, v145
	v_cvt_pk_bf16_f32 v143, v150, v151
	v_addc_co_u32_e32 v137, vcc, 0, v131, vcc
	global_store_dwordx4 v[136:137], v[140:143], off
	v_pk_mul_f32 v[136:137], v[22:23], v[132:133] op_sel_hi:[1,0]
	s_mov_b32 s0, 0x28000
	v_mul_f32_e32 v133, 0xbfb8aa3b, v136
	v_exp_f32_e32 v133, v133
	s_nop 0
	v_add_f32_e32 v133, 1.0, v133
	v_rcp_f32_e32 v140, v133
	v_mul_f32_e32 v133, 0xbfb8aa3b, v137
	v_exp_f32_e32 v133, v133
	s_nop 0
	v_add_f32_e32 v133, 1.0, v133
	v_rcp_f32_e32 v141, v133
	s_nop 0
	v_pk_mul_f32 v[136:137], v[136:137], v[140:141]
	v_pk_mul_f32 v[140:141], v[24:25], v[132:133] op_sel_hi:[1,0]
	s_nop 0
	v_mul_f32_e32 v133, 0xbfb8aa3b, v140
	v_exp_f32_e32 v133, v133
	s_nop 0
	v_add_f32_e32 v133, 1.0, v133
	v_rcp_f32_e32 v142, v133
	v_mul_f32_e32 v133, 0xbfb8aa3b, v141
	v_exp_f32_e32 v133, v133
	s_nop 0
	v_add_f32_e32 v133, 1.0, v133
	v_rcp_f32_e32 v143, v133
	s_nop 0
	v_pk_mul_f32 v[142:143], v[140:141], v[142:143]
	v_pk_mul_f32 v[140:141], v[18:19], v[132:133] op_sel_hi:[1,0]
	s_nop 0
	v_mul_f32_e32 v133, 0xbfb8aa3b, v140
	v_exp_f32_e32 v133, v133
	s_nop 0
	v_add_f32_e32 v133, 1.0, v133
	v_rcp_f32_e32 v144, v133
	v_mul_f32_e32 v133, 0xbfb8aa3b, v141
	v_exp_f32_e32 v133, v133
	s_nop 0
	v_add_f32_e32 v133, 1.0, v133
	v_rcp_f32_e32 v145, v133
	v_pk_mul_f32 v[132:133], v[20:21], v[132:133] op_sel_hi:[1,0]
	v_pk_mul_f32 v[144:145], v[140:141], v[144:145]
	v_mul_f32_e32 v139, 0xbfb8aa3b, v132
	v_exp_f32_e32 v139, v139
	s_nop 0
	v_add_f32_e32 v139, 1.0, v139
	v_rcp_f32_e32 v140, v139
	v_mul_f32_e32 v139, 0xbfb8aa3b, v133
	v_exp_f32_e32 v139, v139
	s_nop 0
	v_add_f32_e32 v139, 1.0, v139
	v_rcp_f32_e32 v141, v139
	s_nop 0
	v_pk_mul_f32 v[132:133], v[132:133], v[140:141]
	v_cvt_pk_bf16_f32 v141, v142, v143
	v_cvt_pk_bf16_f32 v143, v132, v133
	ds_read2_b32 v[132:133], v138 offset0:160 offset1:176
	v_cvt_pk_bf16_f32 v140, v136, v137
	v_cvt_pk_bf16_f32 v142, v144, v145
	global_store_dwordx4 v[134:135], v[140:143], off offset:256
	v_lshl_add_u64 v[134:135], v[130:131], 0, s[16:17]
	s_waitcnt lgkmcnt(0)
	v_pk_mul_f32 v[136:137], v[46:47], v[132:133] op_sel_hi:[1,0]
	s_mov_b64 s[16:17], 0x2c000
	s_mov_b32 s32, 0xbfb8aa3b
	v_pk_mul_f32 v[138:139], v[136:137], s[32:33] op_sel_hi:[1,0]
	v_exp_f32_e32 v138, v138
	v_exp_f32_e32 v139, v139
	s_nop 0
	v_pk_add_f32 v[138:139], v[138:139], 1.0 op_sel_hi:[1,0]
	v_rcp_f32_e32 v138, v138
	v_rcp_f32_e32 v139, v139
	s_nop 0
	v_pk_mul_f32 v[136:137], v[136:137], v[138:139]
	v_pk_mul_f32 v[138:139], v[48:49], v[132:133] op_sel_hi:[1,0]
	v_cvt_pk_bf16_f32 v136, v136, v137
	v_pk_mul_f32 v[140:141], v[138:139], s[32:33] op_sel_hi:[1,0]
	v_exp_f32_e32 v140, v140
	v_exp_f32_e32 v141, v141
	s_nop 0
	v_pk_add_f32 v[140:141], v[140:141], 1.0 op_sel_hi:[1,0]
	v_rcp_f32_e32 v140, v140
	v_rcp_f32_e32 v141, v141
	s_nop 0
	v_pk_mul_f32 v[138:139], v[138:139], v[140:141]
	v_pk_mul_f32 v[140:141], v[42:43], v[132:133] op_sel_hi:[1,0]
	v_cvt_pk_bf16_f32 v137, v138, v139
	v_pk_mul_f32 v[142:143], v[140:141], s[32:33] op_sel_hi:[1,0]
	v_exp_f32_e32 v142, v142
	v_exp_f32_e32 v143, v143
	s_nop 0
	v_pk_add_f32 v[142:143], v[142:143], 1.0 op_sel_hi:[1,0]
	v_rcp_f32_e32 v142, v142
	v_rcp_f32_e32 v143, v143
	s_nop 0
	v_pk_mul_f32 v[140:141], v[140:141], v[142:143]
	v_pk_mul_f32 v[142:143], v[44:45], v[132:133] op_sel_hi:[1,0]
	v_cvt_pk_bf16_f32 v138, v140, v141
	v_pk_mul_f32 v[144:145], v[142:143], s[32:33] op_sel_hi:[1,0]
	v_exp_f32_e32 v144, v144
	v_exp_f32_e32 v145, v145
	v_add_co_u32_e32 v140, vcc, s0, v130
	v_pk_add_f32 v[144:145], v[144:145], 1.0 op_sel_hi:[1,0]
	v_rcp_f32_e32 v144, v144
	v_rcp_f32_e32 v145, v145
	v_addc_co_u32_e32 v141, vcc, 0, v131, vcc
	s_mov_b32 s0, 0x2c000
	v_pk_mul_f32 v[142:143], v[142:143], v[144:145]
	s_nop 0
	v_cvt_pk_bf16_f32 v139, v142, v143
	global_store_dwordx4 v[140:141], v[136:139], off
	s_nop 1
	v_pk_mul_f32 v[136:137], v[14:15], v[132:133] op_sel_hi:[1,0]
	s_nop 0
	v_pk_mul_f32 v[138:139], v[136:137], s[32:33] op_sel_hi:[1,0]
	v_exp_f32_e32 v138, v138
	v_exp_f32_e32 v139, v139
	s_nop 0
	v_pk_add_f32 v[138:139], v[138:139], 1.0 op_sel_hi:[1,0]
	v_rcp_f32_e32 v138, v138
	v_rcp_f32_e32 v139, v139
	s_nop 0
	v_pk_mul_f32 v[136:137], v[136:137], v[138:139]
	v_pk_mul_f32 v[138:139], v[16:17], v[132:133] op_sel_hi:[1,0]
	v_cvt_pk_bf16_f32 v136, v136, v137
	v_pk_mul_f32 v[140:141], v[138:139], s[32:33] op_sel_hi:[1,0]
	v_exp_f32_e32 v140, v140
	v_exp_f32_e32 v141, v141
	s_nop 0
	v_pk_add_f32 v[140:141], v[140:141], 1.0 op_sel_hi:[1,0]
	v_rcp_f32_e32 v140, v140
	v_rcp_f32_e32 v141, v141
	s_nop 0
	v_pk_mul_f32 v[138:139], v[138:139], v[140:141]
	v_pk_mul_f32 v[140:141], v[10:11], v[132:133] op_sel_hi:[1,0]
	v_cvt_pk_bf16_f32 v137, v138, v139
	v_pk_mul_f32 v[142:143], v[140:141], s[32:33] op_sel_hi:[1,0]
	v_exp_f32_e32 v142, v142
	v_exp_f32_e32 v143, v143
	s_nop 0
	v_pk_add_f32 v[142:143], v[142:143], 1.0 op_sel_hi:[1,0]
	v_rcp_f32_e32 v142, v142
	v_rcp_f32_e32 v143, v143
	s_nop 0
	v_pk_mul_f32 v[140:141], v[140:141], v[142:143]
	v_pk_mul_f32 v[142:143], v[12:13], v[132:133] op_sel_hi:[1,0]
	v_cvt_pk_bf16_f32 v138, v140, v141
	v_mul_f32_e32 v132, 0xbfb8aa3b, v142
	v_exp_f32_e32 v132, v132
	s_nop 0
	v_add_f32_e32 v132, 1.0, v132
	v_rcp_f32_e32 v144, v132
	v_mul_f32_e32 v132, 0xbfb8aa3b, v143
	v_exp_f32_e32 v132, v132
	s_nop 0
	v_add_f32_e32 v132, 1.0, v132
	v_rcp_f32_e32 v145, v132
	v_mov_b32_e32 v132, v133
	v_pk_mul_f32 v[142:143], v[142:143], v[144:145]
	s_nop 0
	v_cvt_pk_bf16_f32 v139, v142, v143
	global_store_dwordx4 v[134:135], v[136:139], off offset:256
	v_lshl_add_u64 v[134:135], v[130:131], 0, s[16:17]
	v_add_co_u32_e32 v130, vcc, s0, v130
	v_pk_mul_f32 v[136:137], v[38:39], v[132:133] op_sel_hi:[1,0]
	s_nop 0
	v_addc_co_u32_e32 v131, vcc, 0, v131, vcc
	v_mul_f32_e32 v133, 0xbfb8aa3b, v136
	v_exp_f32_e32 v133, v133
	s_nop 0
	v_add_f32_e32 v133, 1.0, v133
	v_rcp_f32_e32 v138, v133
	v_mul_f32_e32 v133, 0xbfb8aa3b, v137
	v_exp_f32_e32 v133, v133
	s_nop 0
	v_add_f32_e32 v133, 1.0, v133
	v_rcp_f32_e32 v139, v133
	s_nop 0
	v_pk_mul_f32 v[136:137], v[136:137], v[138:139]
	v_pk_mul_f32 v[138:139], v[40:41], v[132:133] op_sel_hi:[1,0]
	v_cvt_pk_bf16_f32 v136, v136, v137
	v_mul_f32_e32 v133, 0xbfb8aa3b, v138
	v_exp_f32_e32 v133, v133
	s_nop 0
	v_add_f32_e32 v133, 1.0, v133
	v_rcp_f32_e32 v140, v133
	v_mul_f32_e32 v133, 0xbfb8aa3b, v139
	v_exp_f32_e32 v133, v133
	s_nop 0
	v_add_f32_e32 v133, 1.0, v133
	v_rcp_f32_e32 v141, v133
	s_nop 0
	v_pk_mul_f32 v[138:139], v[138:139], v[140:141]
	v_pk_mul_f32 v[140:141], v[34:35], v[132:133] op_sel_hi:[1,0]
	v_cvt_pk_bf16_f32 v137, v138, v139
	v_mul_f32_e32 v133, 0xbfb8aa3b, v140
	v_exp_f32_e32 v133, v133
	s_nop 0
	v_add_f32_e32 v133, 1.0, v133
	v_rcp_f32_e32 v142, v133
	v_mul_f32_e32 v133, 0xbfb8aa3b, v141
	v_exp_f32_e32 v133, v133
	s_nop 0
	v_add_f32_e32 v133, 1.0, v133
	v_rcp_f32_e32 v143, v133
	s_nop 0
	v_pk_mul_f32 v[140:141], v[140:141], v[142:143]
	v_pk_mul_f32 v[142:143], v[36:37], v[132:133] op_sel_hi:[1,0]
	v_cvt_pk_bf16_f32 v138, v140, v141
	v_mul_f32_e32 v133, 0xbfb8aa3b, v142
	v_exp_f32_e32 v133, v133
	s_nop 0
	v_add_f32_e32 v133, 1.0, v133
	v_rcp_f32_e32 v144, v133
	v_mul_f32_e32 v133, 0xbfb8aa3b, v143
	v_exp_f32_e32 v133, v133
	s_nop 0
	v_add_f32_e32 v133, 1.0, v133
	v_rcp_f32_e32 v145, v133
	s_nop 0
	v_pk_mul_f32 v[142:143], v[142:143], v[144:145]
	s_nop 0
	v_cvt_pk_bf16_f32 v139, v142, v143
	global_store_dwordx4 v[130:131], v[136:139], off
	v_pk_mul_f32 v[130:131], v[6:7], v[132:133] op_sel_hi:[1,0]
	s_nop 0
	v_mul_f32_e32 v133, 0xbfb8aa3b, v130
	v_exp_f32_e32 v133, v133
	s_nop 0
	v_add_f32_e32 v133, 1.0, v133
	v_rcp_f32_e32 v136, v133
	v_mul_f32_e32 v133, 0xbfb8aa3b, v131
	v_exp_f32_e32 v133, v133
	s_nop 0
	v_add_f32_e32 v133, 1.0, v133
	v_rcp_f32_e32 v137, v133
	s_nop 0
	v_pk_mul_f32 v[130:131], v[130:131], v[136:137]
	v_pk_mul_f32 v[136:137], v[8:9], v[132:133] op_sel_hi:[1,0]
	v_cvt_pk_bf16_f32 v130, v130, v131
	v_mul_f32_e32 v133, 0xbfb8aa3b, v136
	v_exp_f32_e32 v133, v133
	s_nop 0
	v_add_f32_e32 v133, 1.0, v133
	v_rcp_f32_e32 v138, v133
	v_mul_f32_e32 v133, 0xbfb8aa3b, v137
	v_exp_f32_e32 v133, v133
	s_nop 0
	v_add_f32_e32 v133, 1.0, v133
	v_rcp_f32_e32 v139, v133
	s_nop 0
	v_pk_mul_f32 v[136:137], v[136:137], v[138:139]
	v_pk_mul_f32 v[138:139], v[2:3], v[132:133] op_sel_hi:[1,0]
	v_cvt_pk_bf16_f32 v131, v136, v137
	v_mul_f32_e32 v133, 0xbfb8aa3b, v138
	v_exp_f32_e32 v133, v133
	s_nop 0
	v_add_f32_e32 v133, 1.0, v133
	v_rcp_f32_e32 v140, v133
	v_mul_f32_e32 v133, 0xbfb8aa3b, v139
	v_exp_f32_e32 v133, v133
	s_nop 0
	v_add_f32_e32 v133, 1.0, v133
	v_rcp_f32_e32 v141, v133
	v_pk_mul_f32 v[132:133], v[4:5], v[132:133] op_sel_hi:[1,0]
	v_pk_mul_f32 v[138:139], v[138:139], v[140:141]
	v_pk_mul_f32 v[140:141], v[132:133], s[32:33] op_sel_hi:[1,0]
	v_exp_f32_e32 v140, v140
	v_exp_f32_e32 v141, v141
	s_nop 0
	v_pk_add_f32 v[140:141], v[140:141], 1.0 op_sel_hi:[1,0]
	v_rcp_f32_e32 v140, v140
	v_rcp_f32_e32 v141, v141
	s_nop 0
	v_pk_mul_f32 v[140:141], v[132:133], v[140:141]
	v_cvt_pk_bf16_f32 v132, v138, v139
	v_cvt_pk_bf16_f32 v133, v140, v141
	global_store_dwordx4 v[134:135], v[130:133], off offset:256

.LBB0_1942:
	v_lshl_add_u32 v131, s82, 10, v220
	ds_read2_b32 v[134:135], v131 offset1:16
	v_lshl_or_b32 v132, s83, 7, v219
	v_lshl_add_u32 v130, s40, 8, v1
	v_ashrrev_i32_e32 v133, 31, v132
	s_andn2_b64 vcc, exec, s[36:37]
	s_waitcnt lgkmcnt(0)
	v_pk_mul_f32 v[122:123], v[122:123], v[134:135] op_sel_hi:[1,0]
	v_pk_mul_f32 v[126:127], v[126:127], v[134:135] op_sel_hi:[1,0]
	s_mov_b32 s32, 0xbfb8aa3b
	v_pk_mul_f32 v[136:137], v[122:123], s[32:33] op_sel_hi:[1,0]
	v_exp_f32_e32 v136, v136
	v_exp_f32_e32 v137, v137
	v_pk_mul_f32 v[124:125], v[124:125], v[134:135] op_sel_hi:[1,0]
	v_pk_mul_f32 v[114:115], v[114:115], v[134:135] op_sel_hi:[1,0]
	v_pk_add_f32 v[136:137], v[136:137], 1.0 op_sel_hi:[1,0]
	v_rcp_f32_e32 v136, v136
	v_rcp_f32_e32 v137, v137
	v_pk_mul_f32 v[118:119], v[118:119], v[134:135] op_sel_hi:[1,0]
	v_pk_mul_f32 v[116:117], v[116:117], v[134:135] op_sel_hi:[1,0]
	v_pk_mul_f32 v[120:121], v[120:121], v[134:135] op_sel_hi:[1,0]
	v_pk_mul_f32 v[122:123], v[122:123], v[136:137]
	v_pk_mul_f32 v[128:129], v[128:129], v[134:135] op_sel_hi:[1,0]
	v_pk_mul_f32 v[122:123], v[126:127], v[122:123]
	v_pk_mul_f32 v[126:127], v[124:125], s[32:33] op_sel_hi:[1,0]
	v_exp_f32_e32 v126, v126
	v_exp_f32_e32 v127, v127
	s_nop 0
	v_pk_add_f32 v[126:127], v[126:127], 1.0 op_sel_hi:[1,0]
	v_rcp_f32_e32 v126, v126
	v_rcp_f32_e32 v127, v127
	s_nop 0
	v_pk_mul_f32 v[124:125], v[124:125], v[126:127]
	v_pk_mul_f32 v[126:127], v[114:115], s[32:33] op_sel_hi:[1,0]
	v_exp_f32_e32 v126, v126
	v_exp_f32_e32 v127, v127
	v_pk_mul_f32 v[124:125], v[128:129], v[124:125]
	v_pk_add_f32 v[126:127], v[126:127], 1.0 op_sel_hi:[1,0]
	v_rcp_f32_e32 v126, v126
	v_rcp_f32_e32 v127, v127
	s_nop 0
	v_pk_mul_f32 v[114:115], v[114:115], v[126:127]
	s_nop 0
	v_pk_mul_f32 v[114:115], v[118:119], v[114:115]
	v_pk_mul_f32 v[118:119], v[116:117], s[32:33] op_sel_hi:[1,0]
	v_exp_f32_e32 v118, v118
	v_exp_f32_e32 v119, v119
	s_nop 0
	v_pk_add_f32 v[118:119], v[118:119], 1.0 op_sel_hi:[1,0]
	v_rcp_f32_e32 v118, v118
	v_rcp_f32_e32 v119, v119
	s_nop 0
	v_pk_mul_f32 v[116:117], v[116:117], v[118:119]
	s_nop 0
	v_pk_mul_f32 v[116:117], v[120:121], v[116:117]
	v_cvt_pk_bf16_f32 v120, v114, v115
	v_mov_b64_e32 v[114:115], s[54:55]
	v_cvt_pk_bf16_f32 v118, v122, v123
	v_cvt_pk_bf16_f32 v121, v116, v117
	v_mad_i64_i32 v[122:123], s[14:15], v130, s73, v[114:115]
	v_lshlrev_b64 v[116:117], 1, v[132:133]
	v_cvt_pk_bf16_f32 v119, v124, v125
	v_lshl_add_u64 v[122:123], v[122:123], 0, v[116:117]
	global_store_dwordx4 v[122:123], v[118:121], off
	s_nop 1
	v_mov_b32_e32 v118, v135
	v_pk_mul_f32 v[106:107], v[106:107], v[118:119] op_sel_hi:[1,0]
	s_nop 0
	v_mul_f32_e32 v119, 0xbfb8aa3b, v106
	v_exp_f32_e32 v119, v119
	s_nop 0
	v_add_f32_e32 v119, 1.0, v119
	v_rcp_f32_e32 v120, v119
	v_pk_mul_f32 v[110:111], v[110:111], v[118:119] op_sel_hi:[1,0]
	v_mul_f32_e32 v119, 0xbfb8aa3b, v107
	v_exp_f32_e32 v119, v119
	s_nop 0
	v_add_f32_e32 v119, 1.0, v119
	v_rcp_f32_e32 v121, v119
	v_pk_mul_f32 v[108:109], v[108:109], v[118:119] op_sel_hi:[1,0]
	v_pk_mul_f32 v[98:99], v[98:99], v[118:119] op_sel_hi:[1,0]
	v_pk_mul_f32 v[102:103], v[102:103], v[118:119] op_sel_hi:[1,0]
	v_pk_mul_f32 v[106:107], v[106:107], v[120:121]
	v_pk_mul_f32 v[112:113], v[112:113], v[118:119] op_sel_hi:[1,0]
	v_pk_mul_f32 v[106:107], v[110:111], v[106:107]
	v_pk_mul_f32 v[110:111], v[108:109], s[32:33] op_sel_hi:[1,0]
	v_exp_f32_e32 v110, v110
	v_exp_f32_e32 v111, v111
	v_pk_mul_f32 v[104:105], v[104:105], v[118:119] op_sel_hi:[1,0]
	v_pk_add_f32 v[110:111], v[110:111], 1.0 op_sel_hi:[1,0]
	v_rcp_f32_e32 v110, v110
	v_rcp_f32_e32 v111, v111
	s_nop 0
	v_pk_mul_f32 v[108:109], v[108:109], v[110:111]
	v_pk_mul_f32 v[110:111], v[98:99], s[32:33] op_sel_hi:[1,0]
	v_exp_f32_e32 v110, v110
	v_exp_f32_e32 v111, v111
	v_pk_mul_f32 v[108:109], v[112:113], v[108:109]
	v_pk_add_f32 v[110:111], v[110:111], 1.0 op_sel_hi:[1,0]
	v_rcp_f32_e32 v110, v110
	v_rcp_f32_e32 v111, v111
	s_nop 0
	v_pk_mul_f32 v[98:99], v[98:99], v[110:111]
	s_nop 0
	v_pk_mul_f32 v[102:103], v[102:103], v[98:99]
	v_pk_mul_f32 v[98:99], v[100:101], v[118:119] op_sel_hi:[1,0]
	v_or_b32_e32 v110, 16, v130
	v_pk_mul_f32 v[100:101], v[98:99], s[32:33] op_sel_hi:[1,0]
	v_exp_f32_e32 v100, v100
	v_exp_f32_e32 v101, v101
	s_nop 0
	v_pk_add_f32 v[100:101], v[100:101], 1.0 op_sel_hi:[1,0]
	v_rcp_f32_e32 v100, v100
	v_rcp_f32_e32 v101, v101
	s_nop 0
	v_pk_mul_f32 v[98:99], v[98:99], v[100:101]
	s_nop 0
	v_pk_mul_f32 v[104:105], v[104:105], v[98:99]
	v_cvt_pk_bf16_f32 v100, v102, v103
	v_mad_i64_i32 v[102:103], s[14:15], v110, s73, v[114:115]
	v_cvt_pk_bf16_f32 v98, v106, v107
	v_cvt_pk_bf16_f32 v99, v108, v109
	v_cvt_pk_bf16_f32 v101, v104, v105
	v_lshl_add_u64 v[102:103], v[102:103], 0, v[116:117]
	global_store_dwordx4 v[102:103], v[98:101], off
	ds_read2_b32 v[98:99], v131 offset0:32 offset1:48
	s_waitcnt lgkmcnt(0)
	v_pk_mul_f32 v[90:91], v[90:91], v[98:99] op_sel_hi:[1,0]
	s_nop 0
	v_pk_mul_f32 v[100:101], v[90:91], s[32:33] op_sel_hi:[1,0]
	v_exp_f32_e32 v100, v100
	v_exp_f32_e32 v101, v101
	v_pk_mul_f32 v[94:95], v[94:95], v[98:99] op_sel_hi:[1,0]
	v_pk_mul_f32 v[92:93], v[92:93], v[98:99] op_sel_hi:[1,0]
	v_pk_add_f32 v[100:101], v[100:101], 1.0 op_sel_hi:[1,0]
	v_rcp_f32_e32 v100, v100
	v_rcp_f32_e32 v101, v101
	v_pk_mul_f32 v[82:83], v[82:83], v[98:99] op_sel_hi:[1,0]
	v_pk_mul_f32 v[86:87], v[86:87], v[98:99] op_sel_hi:[1,0]
	v_pk_mul_f32 v[96:97], v[96:97], v[98:99] op_sel_hi:[1,0]
	v_pk_mul_f32 v[90:91], v[90:91], v[100:101]
	v_pk_mul_f32 v[88:89], v[88:89], v[98:99] op_sel_hi:[1,0]
	v_pk_mul_f32 v[90:91], v[94:95], v[90:91]
	v_pk_mul_f32 v[94:95], v[92:93], s[32:33] op_sel_hi:[1,0]
	v_exp_f32_e32 v94, v94
	v_exp_f32_e32 v95, v95
	s_nop 0
	v_pk_add_f32 v[94:95], v[94:95], 1.0 op_sel_hi:[1,0]
	v_rcp_f32_e32 v94, v94
	v_rcp_f32_e32 v95, v95
	s_nop 0
	v_pk_mul_f32 v[92:93], v[92:93], v[94:95]
	v_pk_mul_f32 v[94:95], v[82:83], s[32:33] op_sel_hi:[1,0]
	v_exp_f32_e32 v94, v94
	v_exp_f32_e32 v95, v95
	v_pk_mul_f32 v[92:93], v[96:97], v[92:93]
	v_pk_add_f32 v[94:95], v[94:95], 1.0 op_sel_hi:[1,0]
	v_rcp_f32_e32 v94, v94
	v_rcp_f32_e32 v95, v95
	s_nop 0
	v_pk_mul_f32 v[82:83], v[82:83], v[94:95]
	s_nop 0
	v_pk_mul_f32 v[86:87], v[86:87], v[82:83]
	v_pk_mul_f32 v[82:83], v[84:85], v[98:99] op_sel_hi:[1,0]
	v_or_b32_e32 v94, 32, v130
	v_pk_mul_f32 v[84:85], v[82:83], s[32:33] op_sel_hi:[1,0]
	v_exp_f32_e32 v84, v84
	v_exp_f32_e32 v85, v85
	s_nop 0
	v_pk_add_f32 v[84:85], v[84:85], 1.0 op_sel_hi:[1,0]
	v_rcp_f32_e32 v84, v84
	v_rcp_f32_e32 v85, v85
	s_nop 0
	v_pk_mul_f32 v[82:83], v[82:83], v[84:85]
	s_nop 0
	v_pk_mul_f32 v[88:89], v[88:89], v[82:83]
	v_cvt_pk_bf16_f32 v84, v86, v87
	v_mad_i64_i32 v[86:87], s[14:15], v94, s73, v[114:115]
	v_cvt_pk_bf16_f32 v82, v90, v91
	v_cvt_pk_bf16_f32 v83, v92, v93
	v_cvt_pk_bf16_f32 v85, v88, v89
	v_lshl_add_u64 v[86:87], v[86:87], 0, v[116:117]
	global_store_dwordx4 v[86:87], v[82:85], off
	s_nop 1
	v_mov_b32_e32 v82, v99
	v_pk_mul_f32 v[74:75], v[74:75], v[82:83] op_sel_hi:[1,0]
	s_nop 0
	v_mul_f32_e32 v83, 0xbfb8aa3b, v74
	v_exp_f32_e32 v83, v83
	s_nop 0
	v_add_f32_e32 v83, 1.0, v83
	v_rcp_f32_e32 v84, v83
	v_pk_mul_f32 v[78:79], v[78:79], v[82:83] op_sel_hi:[1,0]
	v_mul_f32_e32 v83, 0xbfb8aa3b, v75
	v_exp_f32_e32 v83, v83
	s_nop 0
	v_add_f32_e32 v83, 1.0, v83
	v_rcp_f32_e32 v85, v83
	v_pk_mul_f32 v[76:77], v[76:77], v[82:83] op_sel_hi:[1,0]
	v_pk_mul_f32 v[66:67], v[66:67], v[82:83] op_sel_hi:[1,0]
	v_pk_mul_f32 v[70:71], v[70:71], v[82:83] op_sel_hi:[1,0]
	v_pk_mul_f32 v[74:75], v[74:75], v[84:85]
	v_pk_mul_f32 v[80:81], v[80:81], v[82:83] op_sel_hi:[1,0]
	v_pk_mul_f32 v[74:75], v[78:79], v[74:75]
	v_pk_mul_f32 v[78:79], v[76:77], s[32:33] op_sel_hi:[1,0]
	v_exp_f32_e32 v78, v78
	v_exp_f32_e32 v79, v79
	v_pk_mul_f32 v[72:73], v[72:73], v[82:83] op_sel_hi:[1,0]
	v_pk_add_f32 v[78:79], v[78:79], 1.0 op_sel_hi:[1,0]
	v_rcp_f32_e32 v78, v78
	v_rcp_f32_e32 v79, v79
	s_nop 0
	v_pk_mul_f32 v[76:77], v[76:77], v[78:79]
	v_pk_mul_f32 v[78:79], v[66:67], s[32:33] op_sel_hi:[1,0]
	v_exp_f32_e32 v78, v78
	v_exp_f32_e32 v79, v79
	v_pk_mul_f32 v[76:77], v[80:81], v[76:77]
	v_pk_add_f32 v[78:79], v[78:79], 1.0 op_sel_hi:[1,0]
	v_rcp_f32_e32 v78, v78
	v_rcp_f32_e32 v79, v79
	s_nop 0
	v_pk_mul_f32 v[66:67], v[66:67], v[78:79]
	s_nop 0
	v_pk_mul_f32 v[70:71], v[70:71], v[66:67]
	v_pk_mul_f32 v[66:67], v[68:69], v[82:83] op_sel_hi:[1,0]
	v_or_b32_e32 v78, 48, v130
	v_pk_mul_f32 v[68:69], v[66:67], s[32:33] op_sel_hi:[1,0]
	v_exp_f32_e32 v68, v68
	v_exp_f32_e32 v69, v69
	s_nop 0
	v_pk_add_f32 v[68:69], v[68:69], 1.0 op_sel_hi:[1,0]
	v_rcp_f32_e32 v68, v68
	v_rcp_f32_e32 v69, v69
	s_nop 0
	v_pk_mul_f32 v[66:67], v[66:67], v[68:69]
	s_nop 0
	v_pk_mul_f32 v[72:73], v[72:73], v[66:67]
	v_cvt_pk_bf16_f32 v68, v70, v71
	v_mad_i64_i32 v[70:71], s[14:15], v78, s73, v[114:115]
	v_cvt_pk_bf16_f32 v66, v74, v75
	v_cvt_pk_bf16_f32 v67, v76, v77
	v_cvt_pk_bf16_f32 v69, v72, v73
	v_lshl_add_u64 v[70:71], v[70:71], 0, v[116:117]
	global_store_dwordx4 v[70:71], v[66:69], off
	ds_read2_b32 v[66:67], v131 offset0:128 offset1:144
	v_add_u32_e32 v70, 0x80, v130
	s_waitcnt lgkmcnt(0)
	v_pk_mul_f32 v[58:59], v[58:59], v[66:67] op_sel_hi:[1,0]
	s_nop 0
	v_pk_mul_f32 v[68:69], v[58:59], s[32:33] op_sel_hi:[1,0]
	v_exp_f32_e32 v68, v68
	v_exp_f32_e32 v69, v69
	v_pk_mul_f32 v[62:63], v[62:63], v[66:67] op_sel_hi:[1,0]
	v_pk_mul_f32 v[60:61], v[60:61], v[66:67] op_sel_hi:[1,0]
	v_pk_add_f32 v[68:69], v[68:69], 1.0 op_sel_hi:[1,0]
	v_rcp_f32_e32 v68, v68
	v_rcp_f32_e32 v69, v69
	v_pk_mul_f32 v[50:51], v[50:51], v[66:67] op_sel_hi:[1,0]
	v_pk_mul_f32 v[54:55], v[54:55], v[66:67] op_sel_hi:[1,0]
	v_pk_mul_f32 v[64:65], v[64:65], v[66:67] op_sel_hi:[1,0]
	v_pk_mul_f32 v[58:59], v[58:59], v[68:69]
	v_pk_mul_f32 v[56:57], v[56:57], v[66:67] op_sel_hi:[1,0]
	v_pk_mul_f32 v[58:59], v[62:63], v[58:59]
	v_pk_mul_f32 v[62:63], v[60:61], s[32:33] op_sel_hi:[1,0]
	v_exp_f32_e32 v62, v62
	v_exp_f32_e32 v63, v63
	s_nop 0
	v_pk_add_f32 v[62:63], v[62:63], 1.0 op_sel_hi:[1,0]
	v_rcp_f32_e32 v62, v62
	v_rcp_f32_e32 v63, v63
	s_nop 0
	v_pk_mul_f32 v[60:61], v[60:61], v[62:63]
	v_pk_mul_f32 v[62:63], v[50:51], s[32:33] op_sel_hi:[1,0]
	v_exp_f32_e32 v62, v62
	v_exp_f32_e32 v63, v63
	v_pk_mul_f32 v[60:61], v[64:65], v[60:61]
	v_pk_add_f32 v[62:63], v[62:63], 1.0 op_sel_hi:[1,0]
	v_rcp_f32_e32 v62, v62
	v_rcp_f32_e32 v63, v63
	s_nop 0
	v_pk_mul_f32 v[50:51], v[50:51], v[62:63]
	s_nop 0
	v_pk_mul_f32 v[54:55], v[54:55], v[50:51]
	v_pk_mul_f32 v[50:51], v[52:53], v[66:67] op_sel_hi:[1,0]
	s_nop 0
	v_pk_mul_f32 v[52:53], v[50:51], s[32:33] op_sel_hi:[1,0]
	v_exp_f32_e32 v52, v52
	v_exp_f32_e32 v53, v53
	s_nop 0
	v_pk_add_f32 v[52:53], v[52:53], 1.0 op_sel_hi:[1,0]
	v_rcp_f32_e32 v52, v52
	v_rcp_f32_e32 v53, v53
	s_nop 0
	v_pk_mul_f32 v[50:51], v[50:51], v[52:53]
	s_nop 0
	v_pk_mul_f32 v[56:57], v[56:57], v[50:51]
	v_cvt_pk_bf16_f32 v52, v54, v55
	v_mad_i64_i32 v[54:55], s[14:15], v70, s73, v[114:115]
	v_cvt_pk_bf16_f32 v50, v58, v59
	v_cvt_pk_bf16_f32 v51, v60, v61
	v_cvt_pk_bf16_f32 v53, v56, v57
	v_lshl_add_u64 v[54:55], v[54:55], 0, v[116:117]
	global_store_dwordx4 v[54:55], v[50:53], off
	s_nop 1
	v_mov_b32_e32 v50, v67
	v_pk_mul_f32 v[42:43], v[42:43], v[50:51] op_sel_hi:[1,0]
	s_nop 0
	v_mul_f32_e32 v51, 0xbfb8aa3b, v42
	v_exp_f32_e32 v51, v51
	s_nop 0
	v_add_f32_e32 v51, 1.0, v51
	v_rcp_f32_e32 v52, v51
	v_pk_mul_f32 v[46:47], v[46:47], v[50:51] op_sel_hi:[1,0]
	v_mul_f32_e32 v51, 0xbfb8aa3b, v43
	v_exp_f32_e32 v51, v51
	s_nop 0
	v_add_f32_e32 v51, 1.0, v51
	v_rcp_f32_e32 v53, v51
	v_pk_mul_f32 v[44:45], v[44:45], v[50:51] op_sel_hi:[1,0]
	v_pk_mul_f32 v[34:35], v[34:35], v[50:51] op_sel_hi:[1,0]
	v_pk_mul_f32 v[38:39], v[38:39], v[50:51] op_sel_hi:[1,0]
	v_pk_mul_f32 v[42:43], v[42:43], v[52:53]
	v_pk_mul_f32 v[48:49], v[48:49], v[50:51] op_sel_hi:[1,0]
	v_pk_mul_f32 v[42:43], v[46:47], v[42:43]
	v_pk_mul_f32 v[46:47], v[44:45], s[32:33] op_sel_hi:[1,0]
	v_exp_f32_e32 v46, v46
	v_exp_f32_e32 v47, v47
	v_pk_mul_f32 v[40:41], v[40:41], v[50:51] op_sel_hi:[1,0]
	v_pk_add_f32 v[46:47], v[46:47], 1.0 op_sel_hi:[1,0]
	v_rcp_f32_e32 v46, v46
	v_rcp_f32_e32 v47, v47
	s_nop 0
	v_pk_mul_f32 v[44:45], v[44:45], v[46:47]
	v_pk_mul_f32 v[46:47], v[34:35], s[32:33] op_sel_hi:[1,0]
	v_exp_f32_e32 v46, v46
	v_exp_f32_e32 v47, v47
	v_pk_mul_f32 v[44:45], v[48:49], v[44:45]
	v_pk_add_f32 v[46:47], v[46:47], 1.0 op_sel_hi:[1,0]
	v_rcp_f32_e32 v46, v46
	v_rcp_f32_e32 v47, v47
	s_nop 0
	v_pk_mul_f32 v[34:35], v[34:35], v[46:47]
	s_nop 0
	v_pk_mul_f32 v[38:39], v[38:39], v[34:35]
	v_pk_mul_f32 v[34:35], v[36:37], v[50:51] op_sel_hi:[1,0]
	v_add_u32_e32 v46, 0x90, v130
	v_pk_mul_f32 v[36:37], v[34:35], s[32:33] op_sel_hi:[1,0]
	v_exp_f32_e32 v36, v36
	v_exp_f32_e32 v37, v37
	s_nop 0
	v_pk_add_f32 v[36:37], v[36:37], 1.0 op_sel_hi:[1,0]
	v_rcp_f32_e32 v36, v36
	v_rcp_f32_e32 v37, v37
	s_nop 0
	v_pk_mul_f32 v[34:35], v[34:35], v[36:37]
	s_nop 0
	v_pk_mul_f32 v[40:41], v[40:41], v[34:35]
	v_cvt_pk_bf16_f32 v36, v38, v39
	v_mad_i64_i32 v[38:39], s[14:15], v46, s73, v[114:115]
	v_cvt_pk_bf16_f32 v34, v42, v43
	v_cvt_pk_bf16_f32 v35, v44, v45
	v_cvt_pk_bf16_f32 v37, v40, v41
	v_lshl_add_u64 v[38:39], v[38:39], 0, v[116:117]
	global_store_dwordx4 v[38:39], v[34:37], off
	ds_read2_b32 v[34:35], v131 offset0:160 offset1:176
	s_waitcnt lgkmcnt(0)
	v_pk_mul_f32 v[26:27], v[26:27], v[34:35] op_sel_hi:[1,0]
	s_nop 0
	v_pk_mul_f32 v[36:37], v[26:27], s[32:33] op_sel_hi:[1,0]
	v_exp_f32_e32 v36, v36
	v_exp_f32_e32 v37, v37
	v_pk_mul_f32 v[30:31], v[30:31], v[34:35] op_sel_hi:[1,0]
	v_pk_mul_f32 v[28:29], v[28:29], v[34:35] op_sel_hi:[1,0]
	v_pk_add_f32 v[36:37], v[36:37], 1.0 op_sel_hi:[1,0]
	v_rcp_f32_e32 v36, v36
	v_rcp_f32_e32 v37, v37
	v_pk_mul_f32 v[18:19], v[18:19], v[34:35] op_sel_hi:[1,0]
	v_pk_mul_f32 v[22:23], v[22:23], v[34:35] op_sel_hi:[1,0]
	v_pk_mul_f32 v[32:33], v[32:33], v[34:35] op_sel_hi:[1,0]
	v_pk_mul_f32 v[26:27], v[26:27], v[36:37]
	v_pk_mul_f32 v[24:25], v[24:25], v[34:35] op_sel_hi:[1,0]
	v_pk_mul_f32 v[26:27], v[30:31], v[26:27]
	v_pk_mul_f32 v[30:31], v[28:29], s[32:33] op_sel_hi:[1,0]
	v_exp_f32_e32 v30, v30
	v_exp_f32_e32 v31, v31
	s_nop 0
	v_pk_add_f32 v[30:31], v[30:31], 1.0 op_sel_hi:[1,0]
	v_rcp_f32_e32 v30, v30
	v_rcp_f32_e32 v31, v31
	s_nop 0
	v_pk_mul_f32 v[28:29], v[28:29], v[30:31]
	v_pk_mul_f32 v[30:31], v[18:19], s[32:33] op_sel_hi:[1,0]
	v_exp_f32_e32 v30, v30
	v_exp_f32_e32 v31, v31
	v_pk_mul_f32 v[28:29], v[32:33], v[28:29]
	v_pk_add_f32 v[30:31], v[30:31], 1.0 op_sel_hi:[1,0]
	v_rcp_f32_e32 v30, v30
	v_rcp_f32_e32 v31, v31
	s_nop 0
	v_pk_mul_f32 v[18:19], v[18:19], v[30:31]
	s_nop 0
	v_pk_mul_f32 v[22:23], v[22:23], v[18:19]
	v_pk_mul_f32 v[18:19], v[20:21], v[34:35] op_sel_hi:[1,0]
	v_add_u32_e32 v30, 0xa0, v130
	v_pk_mul_f32 v[20:21], v[18:19], s[32:33] op_sel_hi:[1,0]
	v_exp_f32_e32 v20, v20
	v_exp_f32_e32 v21, v21
	s_nop 0
	v_pk_add_f32 v[20:21], v[20:21], 1.0 op_sel_hi:[1,0]
	v_rcp_f32_e32 v20, v20
	v_rcp_f32_e32 v21, v21
	s_nop 0
	v_pk_mul_f32 v[18:19], v[18:19], v[20:21]
	s_nop 0
	v_pk_mul_f32 v[24:25], v[24:25], v[18:19]
	v_cvt_pk_bf16_f32 v20, v22, v23
	v_mad_i64_i32 v[22:23], s[14:15], v30, s73, v[114:115]
	v_cvt_pk_bf16_f32 v18, v26, v27
	v_cvt_pk_bf16_f32 v19, v28, v29
	v_cvt_pk_bf16_f32 v21, v24, v25
	v_lshl_add_u64 v[22:23], v[22:23], 0, v[116:117]
	global_store_dwordx4 v[22:23], v[18:21], off
	s_nop 1
	v_mov_b32_e32 v18, v35
	v_pk_mul_f32 v[10:11], v[10:11], v[18:19] op_sel_hi:[1,0]
	s_nop 0
	v_mul_f32_e32 v19, 0xbfb8aa3b, v10
	v_exp_f32_e32 v19, v19
	s_nop 0
	v_add_f32_e32 v19, 1.0, v19
	v_rcp_f32_e32 v20, v19
	v_pk_mul_f32 v[14:15], v[14:15], v[18:19] op_sel_hi:[1,0]
	v_mul_f32_e32 v19, 0xbfb8aa3b, v11
	v_exp_f32_e32 v19, v19
	s_nop 0
	v_add_f32_e32 v19, 1.0, v19
	v_rcp_f32_e32 v21, v19
	v_pk_mul_f32 v[12:13], v[12:13], v[18:19] op_sel_hi:[1,0]
	v_pk_mul_f32 v[2:3], v[2:3], v[18:19] op_sel_hi:[1,0]
	v_pk_mul_f32 v[6:7], v[6:7], v[18:19] op_sel_hi:[1,0]
	v_pk_mul_f32 v[10:11], v[10:11], v[20:21]
	v_pk_mul_f32 v[16:17], v[16:17], v[18:19] op_sel_hi:[1,0]
	v_pk_mul_f32 v[10:11], v[14:15], v[10:11]
	v_pk_mul_f32 v[14:15], v[12:13], s[32:33] op_sel_hi:[1,0]
	v_exp_f32_e32 v14, v14
	v_exp_f32_e32 v15, v15
	v_pk_mul_f32 v[8:9], v[8:9], v[18:19] op_sel_hi:[1,0]
	v_pk_add_f32 v[14:15], v[14:15], 1.0 op_sel_hi:[1,0]
	v_rcp_f32_e32 v14, v14
	v_rcp_f32_e32 v15, v15
	s_nop 0
	v_pk_mul_f32 v[12:13], v[12:13], v[14:15]
	v_pk_mul_f32 v[14:15], v[2:3], s[32:33] op_sel_hi:[1,0]
	v_exp_f32_e32 v14, v14
	v_exp_f32_e32 v15, v15
	v_pk_mul_f32 v[12:13], v[16:17], v[12:13]
	v_pk_add_f32 v[14:15], v[14:15], 1.0 op_sel_hi:[1,0]
	v_rcp_f32_e32 v14, v14
	v_rcp_f32_e32 v15, v15
	s_nop 0
	v_pk_mul_f32 v[2:3], v[2:3], v[14:15]
	s_nop 0
	v_pk_mul_f32 v[6:7], v[6:7], v[2:3]
	v_pk_mul_f32 v[2:3], v[4:5], v[18:19] op_sel_hi:[1,0]
	v_add_u32_e32 v14, 0xb0, v130
	v_pk_mul_f32 v[4:5], v[2:3], s[32:33] op_sel_hi:[1,0]
	v_exp_f32_e32 v4, v4
	v_exp_f32_e32 v5, v5
	s_nop 0
	v_pk_add_f32 v[4:5], v[4:5], 1.0 op_sel_hi:[1,0]
	v_rcp_f32_e32 v4, v4
	v_rcp_f32_e32 v5, v5
	s_nop 0
	v_pk_mul_f32 v[2:3], v[2:3], v[4:5]
	s_nop 0
	v_pk_mul_f32 v[8:9], v[8:9], v[2:3]
	v_cvt_pk_bf16_f32 v4, v6, v7
	v_mad_i64_i32 v[6:7], s[14:15], v14, s73, v[114:115]
	v_cvt_pk_bf16_f32 v2, v10, v11
	v_cvt_pk_bf16_f32 v3, v12, v13
	v_cvt_pk_bf16_f32 v5, v8, v9
	v_lshl_add_u64 v[6:7], v[6:7], 0, v[116:117]
	s_mov_b64 s[14:15], -1
	global_store_dwordx4 v[6:7], v[2:5], off
	s_cbranch_vccnz .LBB0_1923
	s_andn2_b64 vcc, exec, s[0:1]
	s_cbranch_vccnz .LBB0_1922
	s_barrier
	s_branch .LBB0_1922
